# v14 plus: per-block s_setprio toggles in the GEMM K-loops removed
# speedup vs baseline: 1.0377x; 1.0030x over previous
.LBB0_305:
	ds_read_b128 v[146:149], v171
	ds_read_b128 v[150:153], v171 offset:1024
	ds_read_b128 v[154:157], v171 offset:2048
	ds_read_b128 v[158:161], v171 offset:3072
	ds_read_b128 v[174:177], v172
	ds_read_b128 v[178:181], v172 offset:1024
	ds_read_b128 v[182:185], v172 offset:2048
	ds_read_b128 v[186:189], v172 offset:3072
	s_add_u32 s40, s8, 0xfffc0080
	s_addc_u32 s41, s9, -1
	s_cmp_eq_u32 s69, 12
	s_cselect_b32 s51, s7, s41
	s_cselect_b32 s50, s23, s40
	s_cselect_b32 s49, s35, s53
	s_cselect_b32 s48, s37, s52
	v_lshl_add_u64 v[162:163], s[8:9], 0, v[140:141]
	s_add_i32 m0, s55, 0xc000
	ds_read_b128 v[190:193], v173
	ds_read_b128 v[194:197], v173 offset:1024
	ds_read_b128 v[198:201], v173 offset:2048
	ds_read_b128 v[202:205], v173 offset:3072
	ds_read_b128 v[206:209], v173 offset:4096
	ds_read_b128 v[210:213], v173 offset:5120
	ds_read_b128 v[214:217], v173 offset:6144
	ds_read_b128 v[218:221], v173 offset:7168
	global_load_lds_dwordx4 v[162:163], off
	v_lshl_add_u64 v[162:163], s[8:9], 0, v[138:139]
	s_add_i32 m0, s55, 0xe000
	s_nop 0
	global_load_lds_dwordx4 v[162:163], off
	s_waitcnt vmcnt(8)
	s_waitcnt lgkmcnt(0)
	s_barrier
	s_waitcnt lgkmcnt(0)
	v_mfma_f32_16x16x32_bf16 v[124:127], v[146:149], v[190:193], v[124:127]
	v_mfma_f32_16x16x32_bf16 v[120:123], v[154:157], v[190:193], v[120:123]
	v_mfma_f32_16x16x32_bf16 v[108:111], v[146:149], v[198:201], v[108:111]
	v_mfma_f32_16x16x32_bf16 v[104:107], v[154:157], v[198:201], v[104:107]
	v_mfma_f32_16x16x32_bf16 v[92:95], v[146:149], v[206:209], v[92:95]
	v_mfma_f32_16x16x32_bf16 v[88:91], v[154:157], v[206:209], v[88:91]
	v_mfma_f32_16x16x32_bf16 v[76:79], v[146:149], v[214:217], v[76:79]
	v_mfma_f32_16x16x32_bf16 v[72:75], v[154:157], v[214:217], v[72:75]
	v_mfma_f32_16x16x32_bf16 v[124:127], v[150:153], v[194:197], v[124:127]
	v_mfma_f32_16x16x32_bf16 v[120:123], v[158:161], v[194:197], v[120:123]
	v_mfma_f32_16x16x32_bf16 v[108:111], v[150:153], v[202:205], v[108:111]
	v_mfma_f32_16x16x32_bf16 v[104:107], v[158:161], v[202:205], v[104:107]
	v_mfma_f32_16x16x32_bf16 v[92:95], v[150:153], v[210:213], v[92:95]
	v_mfma_f32_16x16x32_bf16 v[88:91], v[158:161], v[210:213], v[88:91]
	v_mfma_f32_16x16x32_bf16 v[76:79], v[150:153], v[218:221], v[76:79]
	v_mfma_f32_16x16x32_bf16 v[72:75], v[158:161], v[218:221], v[72:75]
	v_mfma_f32_16x16x32_bf16 v[116:119], v[174:177], v[190:193], v[116:119]
	v_mfma_f32_16x16x32_bf16 v[112:115], v[182:185], v[190:193], v[112:115]
	v_mfma_f32_16x16x32_bf16 v[100:103], v[174:177], v[198:201], v[100:103]
	v_mfma_f32_16x16x32_bf16 v[96:99], v[182:185], v[198:201], v[96:99]
	v_mfma_f32_16x16x32_bf16 v[84:87], v[174:177], v[206:209], v[84:87]
	v_mfma_f32_16x16x32_bf16 v[80:83], v[182:185], v[206:209], v[80:83]
	v_mfma_f32_16x16x32_bf16 v[68:71], v[174:177], v[214:217], v[68:71]
	v_mfma_f32_16x16x32_bf16 v[64:67], v[182:185], v[214:217], v[64:67]
	v_mfma_f32_16x16x32_bf16 v[116:119], v[178:181], v[194:197], v[116:119]
	v_mfma_f32_16x16x32_bf16 v[112:115], v[186:189], v[194:197], v[112:115]
	v_mfma_f32_16x16x32_bf16 v[100:103], v[178:181], v[202:205], v[100:103]
	v_mfma_f32_16x16x32_bf16 v[96:99], v[186:189], v[202:205], v[96:99]
	v_mfma_f32_16x16x32_bf16 v[84:87], v[178:181], v[210:213], v[84:87]
	v_mfma_f32_16x16x32_bf16 v[80:83], v[186:189], v[210:213], v[80:83]
	v_mfma_f32_16x16x32_bf16 v[68:71], v[178:181], v[218:221], v[68:71]
	v_mfma_f32_16x16x32_bf16 v[64:67], v[186:189], v[218:221], v[64:67]
	s_barrier
	s_add_i32 s40, s63, s54
	v_lshl_add_u64 v[162:163], s[48:49], 0, v[130:131]
	s_mov_b32 m0, s40
	ds_read_b128 v[190:193], v173 offset:16384
	ds_read_b128 v[194:197], v173 offset:17408
	ds_read_b128 v[198:201], v173 offset:18432
	ds_read_b128 v[202:205], v173 offset:19456
	ds_read_b128 v[206:209], v173 offset:20480
	ds_read_b128 v[210:213], v173 offset:21504
	ds_read_b128 v[214:217], v173 offset:22528
	ds_read_b128 v[218:221], v173 offset:23552
	global_load_lds_dwordx4 v[162:163], off
	s_add_i32 m0, s40, 0x2000
	s_add_u32 s40, s48, 0x40000
	v_lshl_add_u64 v[222:223], s[48:49], 0, v[134:135]
	s_addc_u32 s41, s49, 0
	s_add_i32 s70, s64, s54
	global_load_lds_dwordx4 v[222:223], off
	v_lshl_add_u64 v[224:225], s[40:41], 0, v[130:131]
	s_mov_b32 m0, s70
	v_lshl_add_u64 v[226:227], s[50:51], 0, v[132:133]
	global_load_lds_dwordx4 v[224:225], off
	v_lshl_add_u64 v[224:225], s[40:41], 0, v[134:135]
	s_add_i32 m0, s70, 0x2000
	s_nop 0
	global_load_lds_dwordx4 v[224:225], off
	v_lshl_add_u64 v[224:225], s[50:51], 0, v[128:129]
	s_mov_b32 m0, s55
	s_nop 0
	global_load_lds_dwordx4 v[224:225], off
	s_mov_b32 m0, s56
	s_nop 0
	global_load_lds_dwordx4 v[226:227], off
	s_waitcnt vmcnt(8)
	s_waitcnt lgkmcnt(0)
	s_barrier
	s_waitcnt lgkmcnt(0)
	v_mfma_f32_16x16x32_bf16 v[60:63], v[146:149], v[190:193], v[60:63]
	v_mfma_f32_16x16x32_bf16 v[56:59], v[154:157], v[190:193], v[56:59]
	v_mfma_f32_16x16x32_bf16 v[44:47], v[146:149], v[198:201], v[44:47]
	v_mfma_f32_16x16x32_bf16 v[40:43], v[154:157], v[198:201], v[40:43]
	v_mfma_f32_16x16x32_bf16 v[28:31], v[146:149], v[206:209], v[28:31]
	v_mfma_f32_16x16x32_bf16 v[24:27], v[154:157], v[206:209], v[24:27]
	v_mfma_f32_16x16x32_bf16 v[12:15], v[146:149], v[214:217], v[12:15]
	v_mfma_f32_16x16x32_bf16 v[8:11], v[154:157], v[214:217], v[8:11]
	v_mfma_f32_16x16x32_bf16 v[60:63], v[150:153], v[194:197], v[60:63]
	v_mfma_f32_16x16x32_bf16 v[56:59], v[158:161], v[194:197], v[56:59]
	v_mfma_f32_16x16x32_bf16 v[44:47], v[150:153], v[202:205], v[44:47]
	v_mfma_f32_16x16x32_bf16 v[40:43], v[158:161], v[202:205], v[40:43]
	v_mfma_f32_16x16x32_bf16 v[28:31], v[150:153], v[210:213], v[28:31]
	v_mfma_f32_16x16x32_bf16 v[24:27], v[158:161], v[210:213], v[24:27]
	v_mfma_f32_16x16x32_bf16 v[12:15], v[150:153], v[218:221], v[12:15]
	v_mfma_f32_16x16x32_bf16 v[8:11], v[158:161], v[218:221], v[8:11]
	v_mfma_f32_16x16x32_bf16 v[52:55], v[174:177], v[190:193], v[52:55]
	v_mfma_f32_16x16x32_bf16 v[48:51], v[182:185], v[190:193], v[48:51]
	v_mfma_f32_16x16x32_bf16 v[36:39], v[174:177], v[198:201], v[36:39]
	v_mfma_f32_16x16x32_bf16 v[32:35], v[182:185], v[198:201], v[32:35]
	v_mfma_f32_16x16x32_bf16 v[20:23], v[174:177], v[206:209], v[20:23]
	v_mfma_f32_16x16x32_bf16 v[16:19], v[182:185], v[206:209], v[16:19]
	v_mfma_f32_16x16x32_bf16 v[4:7], v[174:177], v[214:217], v[4:7]
	v_mfma_f32_16x16x32_bf16 v[0:3], v[182:185], v[214:217], v[0:3]
	v_mfma_f32_16x16x32_bf16 v[52:55], v[178:181], v[194:197], v[52:55]
	v_mfma_f32_16x16x32_bf16 v[48:51], v[186:189], v[194:197], v[48:51]
	v_mfma_f32_16x16x32_bf16 v[36:39], v[178:181], v[202:205], v[36:39]
	v_mfma_f32_16x16x32_bf16 v[32:35], v[186:189], v[202:205], v[32:35]
	v_mfma_f32_16x16x32_bf16 v[20:23], v[178:181], v[210:213], v[20:23]
	v_mfma_f32_16x16x32_bf16 v[16:19], v[186:189], v[210:213], v[16:19]
	v_mfma_f32_16x16x32_bf16 v[4:7], v[178:181], v[218:221], v[4:7]
	v_mfma_f32_16x16x32_bf16 v[0:3], v[186:189], v[218:221], v[0:3]
	s_barrier
	s_add_i32 s70, 0, 0x18000
	v_add_u32_e32 v136, s70, v165
	s_add_i32 s71, 0, 0x1c000
	ds_read_b128 v[146:149], v136
	ds_read_b128 v[150:153], v136 offset:1024
	ds_read_b128 v[154:157], v136 offset:2048
	ds_read_b128 v[158:161], v136 offset:3072
	v_add_u32_e32 v136, s71, v165
	ds_read_b128 v[174:177], v136
	ds_read_b128 v[178:181], v136 offset:1024
	ds_read_b128 v[182:185], v136 offset:2048
	ds_read_b128 v[186:189], v136 offset:3072
	s_add_u32 s40, s50, 0x40000
	s_addc_u32 s41, s51, 0
	s_mov_b32 m0, s57
	v_lshl_add_u64 v[228:229], s[40:41], 0, v[128:129]
	ds_read_b128 v[190:193], v173 offset:32768
	ds_read_b128 v[194:197], v173 offset:33792
	ds_read_b128 v[198:201], v173 offset:34816
	ds_read_b128 v[202:205], v173 offset:35840
	ds_read_b128 v[206:209], v173 offset:36864
	ds_read_b128 v[210:213], v173 offset:37888
	ds_read_b128 v[214:217], v173 offset:38912
	ds_read_b128 v[218:221], v173 offset:39936
	global_load_lds_dwordx4 v[228:229], off
	v_lshl_add_u64 v[228:229], s[40:41], 0, v[132:133]
	s_mov_b32 m0, s58
	s_nop 0
	global_load_lds_dwordx4 v[228:229], off
	s_waitcnt vmcnt(8)
	s_waitcnt lgkmcnt(0)
	s_barrier
	s_waitcnt lgkmcnt(0)
	v_mfma_f32_16x16x32_bf16 v[124:127], v[146:149], v[190:193], v[124:127]
	v_mfma_f32_16x16x32_bf16 v[120:123], v[154:157], v[190:193], v[120:123]
	v_mfma_f32_16x16x32_bf16 v[108:111], v[146:149], v[198:201], v[108:111]
	v_mfma_f32_16x16x32_bf16 v[104:107], v[154:157], v[198:201], v[104:107]
	v_mfma_f32_16x16x32_bf16 v[92:95], v[146:149], v[206:209], v[92:95]
	v_mfma_f32_16x16x32_bf16 v[88:91], v[154:157], v[206:209], v[88:91]
	v_mfma_f32_16x16x32_bf16 v[76:79], v[146:149], v[214:217], v[76:79]
	v_mfma_f32_16x16x32_bf16 v[72:75], v[154:157], v[214:217], v[72:75]
	v_mfma_f32_16x16x32_bf16 v[124:127], v[150:153], v[194:197], v[124:127]
	v_mfma_f32_16x16x32_bf16 v[120:123], v[158:161], v[194:197], v[120:123]
	v_mfma_f32_16x16x32_bf16 v[108:111], v[150:153], v[202:205], v[108:111]
	v_mfma_f32_16x16x32_bf16 v[104:107], v[158:161], v[202:205], v[104:107]
	v_mfma_f32_16x16x32_bf16 v[92:95], v[150:153], v[210:213], v[92:95]
	v_mfma_f32_16x16x32_bf16 v[88:91], v[158:161], v[210:213], v[88:91]
	v_mfma_f32_16x16x32_bf16 v[76:79], v[150:153], v[218:221], v[76:79]
	v_mfma_f32_16x16x32_bf16 v[72:75], v[158:161], v[218:221], v[72:75]
	v_mfma_f32_16x16x32_bf16 v[116:119], v[174:177], v[190:193], v[116:119]
	v_mfma_f32_16x16x32_bf16 v[112:115], v[182:185], v[190:193], v[112:115]
	v_mfma_f32_16x16x32_bf16 v[100:103], v[174:177], v[198:201], v[100:103]
	v_mfma_f32_16x16x32_bf16 v[96:99], v[182:185], v[198:201], v[96:99]
	v_mfma_f32_16x16x32_bf16 v[84:87], v[174:177], v[206:209], v[84:87]
	v_mfma_f32_16x16x32_bf16 v[80:83], v[182:185], v[206:209], v[80:83]
	v_mfma_f32_16x16x32_bf16 v[68:71], v[174:177], v[214:217], v[68:71]
	v_mfma_f32_16x16x32_bf16 v[64:67], v[182:185], v[214:217], v[64:67]
	v_mfma_f32_16x16x32_bf16 v[116:119], v[178:181], v[194:197], v[116:119]
	v_mfma_f32_16x16x32_bf16 v[112:115], v[186:189], v[194:197], v[112:115]
	v_mfma_f32_16x16x32_bf16 v[100:103], v[178:181], v[202:205], v[100:103]
	v_mfma_f32_16x16x32_bf16 v[96:99], v[186:189], v[202:205], v[96:99]
	v_mfma_f32_16x16x32_bf16 v[84:87], v[178:181], v[210:213], v[84:87]
	v_mfma_f32_16x16x32_bf16 v[80:83], v[186:189], v[210:213], v[80:83]
	v_mfma_f32_16x16x32_bf16 v[68:71], v[178:181], v[218:221], v[68:71]
	v_mfma_f32_16x16x32_bf16 v[64:67], v[186:189], v[218:221], v[64:67]
	s_barrier
	s_add_i32 s40, s70, s54
	v_lshl_add_u64 v[162:163], v[162:163], 0, s[24:25]
	s_mov_b32 m0, s40
	ds_read_b128 v[190:193], v173 offset:49152
	ds_read_b128 v[194:197], v173 offset:50176
	ds_read_b128 v[198:201], v173 offset:51200
	ds_read_b128 v[202:205], v173 offset:52224
	ds_read_b128 v[206:209], v173 offset:53248
	ds_read_b128 v[210:213], v173 offset:54272
	ds_read_b128 v[214:217], v173 offset:55296
	ds_read_b128 v[218:221], v173 offset:56320
	global_load_lds_dwordx4 v[162:163], off
	s_add_i32 m0, s40, 0x2000
	s_add_u32 s40, s48, 0x40080
	v_lshl_add_u64 v[162:163], v[222:223], 0, s[24:25]
	s_addc_u32 s41, s49, 0
	s_add_i32 s48, s71, s54
	global_load_lds_dwordx4 v[162:163], off
	v_lshl_add_u64 v[162:163], s[40:41], 0, v[130:131]
	s_mov_b32 m0, s48
	s_nop 0
	global_load_lds_dwordx4 v[162:163], off
	v_lshl_add_u64 v[162:163], s[40:41], 0, v[134:135]
	s_add_i32 m0, s48, 0x2000
	s_nop 0
	global_load_lds_dwordx4 v[162:163], off
	v_lshl_add_u64 v[162:163], v[224:225], 0, s[24:25]
	s_mov_b32 m0, s61
	s_nop 0
	global_load_lds_dwordx4 v[162:163], off
	v_lshl_add_u64 v[162:163], v[226:227], 0, s[24:25]
	s_mov_b32 m0, s62
	s_nop 0
	global_load_lds_dwordx4 v[162:163], off
	s_waitcnt vmcnt(8)
	s_waitcnt lgkmcnt(0)
	s_barrier
	s_waitcnt lgkmcnt(0)
	v_mfma_f32_16x16x32_bf16 v[60:63], v[146:149], v[190:193], v[60:63]
	v_mfma_f32_16x16x32_bf16 v[56:59], v[154:157], v[190:193], v[56:59]
	v_mfma_f32_16x16x32_bf16 v[44:47], v[146:149], v[198:201], v[44:47]
	v_mfma_f32_16x16x32_bf16 v[40:43], v[154:157], v[198:201], v[40:43]
	v_mfma_f32_16x16x32_bf16 v[28:31], v[146:149], v[206:209], v[28:31]
	v_mfma_f32_16x16x32_bf16 v[24:27], v[154:157], v[206:209], v[24:27]
	v_mfma_f32_16x16x32_bf16 v[12:15], v[146:149], v[214:217], v[12:15]
	v_mfma_f32_16x16x32_bf16 v[8:11], v[154:157], v[214:217], v[8:11]
	v_mfma_f32_16x16x32_bf16 v[60:63], v[150:153], v[194:197], v[60:63]
	v_mfma_f32_16x16x32_bf16 v[56:59], v[158:161], v[194:197], v[56:59]
	v_mfma_f32_16x16x32_bf16 v[44:47], v[150:153], v[202:205], v[44:47]
	v_mfma_f32_16x16x32_bf16 v[40:43], v[158:161], v[202:205], v[40:43]
	v_mfma_f32_16x16x32_bf16 v[28:31], v[150:153], v[210:213], v[28:31]
	v_mfma_f32_16x16x32_bf16 v[24:27], v[158:161], v[210:213], v[24:27]
	v_mfma_f32_16x16x32_bf16 v[12:15], v[150:153], v[218:221], v[12:15]
	v_mfma_f32_16x16x32_bf16 v[8:11], v[158:161], v[218:221], v[8:11]
	v_mfma_f32_16x16x32_bf16 v[52:55], v[174:177], v[190:193], v[52:55]
	v_mfma_f32_16x16x32_bf16 v[48:51], v[182:185], v[190:193], v[48:51]
	v_mfma_f32_16x16x32_bf16 v[36:39], v[174:177], v[198:201], v[36:39]
	v_mfma_f32_16x16x32_bf16 v[32:35], v[182:185], v[198:201], v[32:35]
	v_mfma_f32_16x16x32_bf16 v[20:23], v[174:177], v[206:209], v[20:23]
	v_mfma_f32_16x16x32_bf16 v[16:19], v[182:185], v[206:209], v[16:19]
	v_mfma_f32_16x16x32_bf16 v[4:7], v[174:177], v[214:217], v[4:7]
	v_mfma_f32_16x16x32_bf16 v[0:3], v[182:185], v[214:217], v[0:3]
	v_mfma_f32_16x16x32_bf16 v[52:55], v[178:181], v[194:197], v[52:55]
	v_mfma_f32_16x16x32_bf16 v[48:51], v[186:189], v[194:197], v[48:51]
	v_mfma_f32_16x16x32_bf16 v[36:39], v[178:181], v[202:205], v[36:39]
	v_mfma_f32_16x16x32_bf16 v[32:35], v[186:189], v[202:205], v[32:35]
	v_mfma_f32_16x16x32_bf16 v[20:23], v[178:181], v[210:213], v[20:23]
	v_mfma_f32_16x16x32_bf16 v[16:19], v[186:189], v[210:213], v[16:19]
	v_mfma_f32_16x16x32_bf16 v[4:7], v[178:181], v[218:221], v[4:7]
	v_mfma_f32_16x16x32_bf16 v[0:3], v[186:189], v[218:221], v[0:3]
	s_barrier
	s_add_i32 s69, s69, 2
	s_add_u32 s52, s52, 0x100
	s_addc_u32 s53, s53, 0
	s_add_u32 s8, s8, 0x100
	s_addc_u32 s9, s9, 0
	s_cmp_gt_u32 s69, 13
	s_cbranch_scc0 .LBB0_305
	s_and_b64 vcc, exec, s[26:27]
	s_cbranch_vccz .LBB0_308
	s_barrier

.LBB0_1162:
	s_add_u32 s26, s24, 0xfffc0080
	s_addc_u32 s27, s25, -1
	s_add_i32 s40, 0, 0x10000
	s_cmp_eq_u32 s52, 12
	s_cselect_b32 s29, s7, s27
	s_cselect_b32 s28, s9, s26
	s_cselect_b32 s27, s17, s31
	s_cselect_b32 s26, s19, s30
	s_add_i32 s56, 0, 0x14000
	v_add_u32_e32 v156, s40, v153
	v_add_u32_e32 v160, s56, v153
	ds_read_b128 v[140:143], v156
	ds_read_b128 v[144:147], v156 offset:1024
	ds_read_b128 v[148:151], v156 offset:2048
	ds_read_b128 v[156:159], v156 offset:3072
	ds_read_b128 v[172:175], v160
	ds_read_b128 v[176:179], v160 offset:1024
	ds_read_b128 v[180:183], v160 offset:2048
	ds_read_b128 v[184:187], v160 offset:3072
	v_lshl_add_u64 v[162:163], s[24:25], 0, v[138:139]
	s_add_i32 m0, s36, 0xc000
	ds_read_b128 v[188:191], v155
	ds_read_b128 v[192:195], v155 offset:1024
	ds_read_b128 v[196:199], v155 offset:2048
	ds_read_b128 v[200:203], v155 offset:3072
	ds_read_b128 v[204:207], v155 offset:4096
	ds_read_b128 v[208:211], v155 offset:5120
	ds_read_b128 v[212:215], v155 offset:6144
	ds_read_b128 v[216:219], v155 offset:7168
	global_load_lds_dwordx4 v[162:163], off
	v_lshl_add_u64 v[162:163], s[24:25], 0, v[136:137]
	s_add_i32 m0, s36, 0xe000
	s_nop 0
	global_load_lds_dwordx4 v[162:163], off
	s_waitcnt vmcnt(8)
	s_waitcnt lgkmcnt(0)
	s_barrier
	s_waitcnt lgkmcnt(0)
	v_mfma_f32_16x16x32_bf16 v[124:127], v[140:143], v[188:191], v[124:127]
	v_mfma_f32_16x16x32_bf16 v[120:123], v[148:151], v[188:191], v[120:123]
	v_mfma_f32_16x16x32_bf16 v[108:111], v[140:143], v[196:199], v[108:111]
	v_mfma_f32_16x16x32_bf16 v[104:107], v[148:151], v[196:199], v[104:107]
	v_mfma_f32_16x16x32_bf16 v[92:95], v[140:143], v[204:207], v[92:95]
	v_mfma_f32_16x16x32_bf16 v[88:91], v[148:151], v[204:207], v[88:91]
	v_mfma_f32_16x16x32_bf16 v[76:79], v[140:143], v[212:215], v[76:79]
	v_mfma_f32_16x16x32_bf16 v[72:75], v[148:151], v[212:215], v[72:75]
	v_mfma_f32_16x16x32_bf16 v[124:127], v[144:147], v[192:195], v[124:127]
	v_mfma_f32_16x16x32_bf16 v[120:123], v[156:159], v[192:195], v[120:123]
	v_mfma_f32_16x16x32_bf16 v[108:111], v[144:147], v[200:203], v[108:111]
	v_mfma_f32_16x16x32_bf16 v[104:107], v[156:159], v[200:203], v[104:107]
	v_mfma_f32_16x16x32_bf16 v[92:95], v[144:147], v[208:211], v[92:95]
	v_mfma_f32_16x16x32_bf16 v[88:91], v[156:159], v[208:211], v[88:91]
	v_mfma_f32_16x16x32_bf16 v[76:79], v[144:147], v[216:219], v[76:79]
	v_mfma_f32_16x16x32_bf16 v[72:75], v[156:159], v[216:219], v[72:75]
	v_mfma_f32_16x16x32_bf16 v[116:119], v[172:175], v[188:191], v[116:119]
	v_mfma_f32_16x16x32_bf16 v[112:115], v[180:183], v[188:191], v[112:115]
	v_mfma_f32_16x16x32_bf16 v[100:103], v[172:175], v[196:199], v[100:103]
	v_mfma_f32_16x16x32_bf16 v[96:99], v[180:183], v[196:199], v[96:99]
	v_mfma_f32_16x16x32_bf16 v[84:87], v[172:175], v[204:207], v[84:87]
	v_mfma_f32_16x16x32_bf16 v[80:83], v[180:183], v[204:207], v[80:83]
	v_mfma_f32_16x16x32_bf16 v[68:71], v[172:175], v[212:215], v[68:71]
	v_mfma_f32_16x16x32_bf16 v[64:67], v[180:183], v[212:215], v[64:67]
	v_mfma_f32_16x16x32_bf16 v[116:119], v[176:179], v[192:195], v[116:119]
	v_mfma_f32_16x16x32_bf16 v[112:115], v[184:187], v[192:195], v[112:115]
	v_mfma_f32_16x16x32_bf16 v[100:103], v[176:179], v[200:203], v[100:103]
	v_mfma_f32_16x16x32_bf16 v[96:99], v[184:187], v[200:203], v[96:99]
	v_mfma_f32_16x16x32_bf16 v[84:87], v[176:179], v[208:211], v[84:87]
	v_mfma_f32_16x16x32_bf16 v[80:83], v[184:187], v[208:211], v[80:83]
	v_mfma_f32_16x16x32_bf16 v[68:71], v[176:179], v[216:219], v[68:71]
	v_mfma_f32_16x16x32_bf16 v[64:67], v[184:187], v[216:219], v[64:67]
	s_barrier
	s_add_i32 s40, s40, s35
	v_lshl_add_u64 v[162:163], s[26:27], 0, v[130:131]
	s_mov_b32 m0, s40
	ds_read_b128 v[188:191], v155 offset:16384
	ds_read_b128 v[192:195], v155 offset:17408
	ds_read_b128 v[196:199], v155 offset:18432
	ds_read_b128 v[200:203], v155 offset:19456
	ds_read_b128 v[204:207], v155 offset:20480
	ds_read_b128 v[208:211], v155 offset:21504
	ds_read_b128 v[212:215], v155 offset:22528
	ds_read_b128 v[216:219], v155 offset:23552
	global_load_lds_dwordx4 v[162:163], off
	s_add_i32 m0, s40, 0x2000
	s_add_u32 s40, s26, 0x40000
	v_lshl_add_u64 v[164:165], s[26:27], 0, v[134:135]
	s_addc_u32 s41, s27, 0
	s_add_i32 s56, s56, s35
	global_load_lds_dwordx4 v[164:165], off
	v_lshl_add_u64 v[168:169], s[40:41], 0, v[130:131]
	s_mov_b32 m0, s56
	v_lshl_add_u64 v[170:171], s[28:29], 0, v[132:133]
	global_load_lds_dwordx4 v[168:169], off
	v_lshl_add_u64 v[168:169], s[40:41], 0, v[134:135]
	s_add_i32 m0, s56, 0x2000
	s_nop 0
	global_load_lds_dwordx4 v[168:169], off
	v_lshl_add_u64 v[168:169], s[28:29], 0, v[128:129]
	s_mov_b32 m0, s36
	s_nop 0
	global_load_lds_dwordx4 v[168:169], off
	s_mov_b32 m0, s37
	s_nop 0
	global_load_lds_dwordx4 v[170:171], off
	s_waitcnt vmcnt(8)
	s_waitcnt lgkmcnt(0)
	s_barrier
	s_waitcnt lgkmcnt(0)
	v_mfma_f32_16x16x32_bf16 v[60:63], v[140:143], v[188:191], v[60:63]
	v_mfma_f32_16x16x32_bf16 v[56:59], v[148:151], v[188:191], v[56:59]
	v_mfma_f32_16x16x32_bf16 v[44:47], v[140:143], v[196:199], v[44:47]
	v_mfma_f32_16x16x32_bf16 v[40:43], v[148:151], v[196:199], v[40:43]
	v_mfma_f32_16x16x32_bf16 v[28:31], v[140:143], v[204:207], v[28:31]
	v_mfma_f32_16x16x32_bf16 v[24:27], v[148:151], v[204:207], v[24:27]
	v_mfma_f32_16x16x32_bf16 v[12:15], v[140:143], v[212:215], v[12:15]
	v_mfma_f32_16x16x32_bf16 v[8:11], v[148:151], v[212:215], v[8:11]
	v_mfma_f32_16x16x32_bf16 v[60:63], v[144:147], v[192:195], v[60:63]
	v_mfma_f32_16x16x32_bf16 v[56:59], v[156:159], v[192:195], v[56:59]
	v_mfma_f32_16x16x32_bf16 v[44:47], v[144:147], v[200:203], v[44:47]
	v_mfma_f32_16x16x32_bf16 v[40:43], v[156:159], v[200:203], v[40:43]
	v_mfma_f32_16x16x32_bf16 v[28:31], v[144:147], v[208:211], v[28:31]
	v_mfma_f32_16x16x32_bf16 v[24:27], v[156:159], v[208:211], v[24:27]
	v_mfma_f32_16x16x32_bf16 v[12:15], v[144:147], v[216:219], v[12:15]
	v_mfma_f32_16x16x32_bf16 v[8:11], v[156:159], v[216:219], v[8:11]
	v_mfma_f32_16x16x32_bf16 v[52:55], v[172:175], v[188:191], v[52:55]
	v_mfma_f32_16x16x32_bf16 v[48:51], v[180:183], v[188:191], v[48:51]
	v_mfma_f32_16x16x32_bf16 v[36:39], v[172:175], v[196:199], v[36:39]
	v_mfma_f32_16x16x32_bf16 v[32:35], v[180:183], v[196:199], v[32:35]
	v_mfma_f32_16x16x32_bf16 v[20:23], v[172:175], v[204:207], v[20:23]
	v_mfma_f32_16x16x32_bf16 v[16:19], v[180:183], v[204:207], v[16:19]
	v_mfma_f32_16x16x32_bf16 v[4:7], v[172:175], v[212:215], v[4:7]
	v_mfma_f32_16x16x32_bf16 v[0:3], v[180:183], v[212:215], v[0:3]
	v_mfma_f32_16x16x32_bf16 v[52:55], v[176:179], v[192:195], v[52:55]
	v_mfma_f32_16x16x32_bf16 v[48:51], v[184:187], v[192:195], v[48:51]
	v_mfma_f32_16x16x32_bf16 v[36:39], v[176:179], v[200:203], v[36:39]
	v_mfma_f32_16x16x32_bf16 v[32:35], v[184:187], v[200:203], v[32:35]
	v_mfma_f32_16x16x32_bf16 v[20:23], v[176:179], v[208:211], v[20:23]
	v_mfma_f32_16x16x32_bf16 v[16:19], v[184:187], v[208:211], v[16:19]
	v_mfma_f32_16x16x32_bf16 v[4:7], v[176:179], v[216:219], v[4:7]
	v_mfma_f32_16x16x32_bf16 v[0:3], v[184:187], v[216:219], v[0:3]
	s_barrier
	s_add_i32 s40, 0, 0x18000
	s_add_i32 s41, 0, 0x1c000
	v_add_u32_e32 v156, s40, v153
	v_add_u32_e32 v160, s41, v153
	ds_read_b128 v[140:143], v156
	ds_read_b128 v[144:147], v156 offset:1024
	ds_read_b128 v[148:151], v156 offset:2048
	ds_read_b128 v[156:159], v156 offset:3072
	ds_read_b128 v[172:175], v160
	ds_read_b128 v[176:179], v160 offset:1024
	ds_read_b128 v[180:183], v160 offset:2048
	ds_read_b128 v[184:187], v160 offset:3072
	s_add_u32 s28, s28, 0x40000
	s_addc_u32 s29, s29, 0
	s_mov_b32 m0, s44
	v_lshl_add_u64 v[220:221], s[28:29], 0, v[128:129]
	ds_read_b128 v[188:191], v155 offset:32768
	ds_read_b128 v[192:195], v155 offset:33792
	ds_read_b128 v[196:199], v155 offset:34816
	ds_read_b128 v[200:203], v155 offset:35840
	ds_read_b128 v[204:207], v155 offset:36864
	ds_read_b128 v[208:211], v155 offset:37888
	ds_read_b128 v[212:215], v155 offset:38912
	ds_read_b128 v[216:219], v155 offset:39936
	global_load_lds_dwordx4 v[220:221], off
	v_lshl_add_u64 v[220:221], s[28:29], 0, v[132:133]
	s_mov_b32 m0, s46
	s_nop 0
	global_load_lds_dwordx4 v[220:221], off
	s_waitcnt vmcnt(8)
	s_waitcnt lgkmcnt(0)
	s_barrier
	s_waitcnt lgkmcnt(0)
	v_mfma_f32_16x16x32_bf16 v[124:127], v[140:143], v[188:191], v[124:127]
	v_mfma_f32_16x16x32_bf16 v[120:123], v[148:151], v[188:191], v[120:123]
	v_mfma_f32_16x16x32_bf16 v[108:111], v[140:143], v[196:199], v[108:111]
	v_mfma_f32_16x16x32_bf16 v[104:107], v[148:151], v[196:199], v[104:107]
	v_mfma_f32_16x16x32_bf16 v[92:95], v[140:143], v[204:207], v[92:95]
	v_mfma_f32_16x16x32_bf16 v[88:91], v[148:151], v[204:207], v[88:91]
	v_mfma_f32_16x16x32_bf16 v[76:79], v[140:143], v[212:215], v[76:79]
	v_mfma_f32_16x16x32_bf16 v[72:75], v[148:151], v[212:215], v[72:75]
	v_mfma_f32_16x16x32_bf16 v[124:127], v[144:147], v[192:195], v[124:127]
	v_mfma_f32_16x16x32_bf16 v[120:123], v[156:159], v[192:195], v[120:123]
	v_mfma_f32_16x16x32_bf16 v[108:111], v[144:147], v[200:203], v[108:111]
	v_mfma_f32_16x16x32_bf16 v[104:107], v[156:159], v[200:203], v[104:107]
	v_mfma_f32_16x16x32_bf16 v[92:95], v[144:147], v[208:211], v[92:95]
	v_mfma_f32_16x16x32_bf16 v[88:91], v[156:159], v[208:211], v[88:91]
	v_mfma_f32_16x16x32_bf16 v[76:79], v[144:147], v[216:219], v[76:79]
	v_mfma_f32_16x16x32_bf16 v[72:75], v[156:159], v[216:219], v[72:75]
	v_mfma_f32_16x16x32_bf16 v[116:119], v[172:175], v[188:191], v[116:119]
	v_mfma_f32_16x16x32_bf16 v[112:115], v[180:183], v[188:191], v[112:115]
	v_mfma_f32_16x16x32_bf16 v[100:103], v[172:175], v[196:199], v[100:103]
	v_mfma_f32_16x16x32_bf16 v[96:99], v[180:183], v[196:199], v[96:99]
	v_mfma_f32_16x16x32_bf16 v[84:87], v[172:175], v[204:207], v[84:87]
	v_mfma_f32_16x16x32_bf16 v[80:83], v[180:183], v[204:207], v[80:83]
	v_mfma_f32_16x16x32_bf16 v[68:71], v[172:175], v[212:215], v[68:71]
	v_mfma_f32_16x16x32_bf16 v[64:67], v[180:183], v[212:215], v[64:67]
	v_mfma_f32_16x16x32_bf16 v[116:119], v[176:179], v[192:195], v[116:119]
	v_mfma_f32_16x16x32_bf16 v[112:115], v[184:187], v[192:195], v[112:115]
	v_mfma_f32_16x16x32_bf16 v[100:103], v[176:179], v[200:203], v[100:103]
	v_mfma_f32_16x16x32_bf16 v[96:99], v[184:187], v[200:203], v[96:99]
	v_mfma_f32_16x16x32_bf16 v[84:87], v[176:179], v[208:211], v[84:87]
	v_mfma_f32_16x16x32_bf16 v[80:83], v[184:187], v[208:211], v[80:83]
	v_mfma_f32_16x16x32_bf16 v[68:71], v[176:179], v[216:219], v[68:71]
	v_mfma_f32_16x16x32_bf16 v[64:67], v[184:187], v[216:219], v[64:67]
	s_barrier
	s_add_i32 s28, s40, s35
	v_lshl_add_u64 v[162:163], v[162:163], 0, s[50:51]
	s_mov_b32 m0, s28
	ds_read_b128 v[188:191], v155 offset:49152
	ds_read_b128 v[192:195], v155 offset:50176
	ds_read_b128 v[196:199], v155 offset:51200
	ds_read_b128 v[200:203], v155 offset:52224
	ds_read_b128 v[204:207], v155 offset:53248
	ds_read_b128 v[208:211], v155 offset:54272
	ds_read_b128 v[212:215], v155 offset:55296
	ds_read_b128 v[216:219], v155 offset:56320
	global_load_lds_dwordx4 v[162:163], off
	s_add_i32 m0, s28, 0x2000
	s_add_u32 s26, s26, 0x40080
	v_lshl_add_u64 v[162:163], v[164:165], 0, s[50:51]
	s_addc_u32 s27, s27, 0
	s_add_i32 s28, s41, s35
	global_load_lds_dwordx4 v[162:163], off
	v_lshl_add_u64 v[162:163], s[26:27], 0, v[130:131]
	s_mov_b32 m0, s28
	s_nop 0
	global_load_lds_dwordx4 v[162:163], off
	v_lshl_add_u64 v[162:163], s[26:27], 0, v[134:135]
	s_add_i32 m0, s28, 0x2000
	s_nop 0
	global_load_lds_dwordx4 v[162:163], off
	v_lshl_add_u64 v[162:163], v[168:169], 0, s[50:51]
	s_mov_b32 m0, s47
	s_nop 0
	global_load_lds_dwordx4 v[162:163], off
	v_lshl_add_u64 v[162:163], v[170:171], 0, s[50:51]
	s_mov_b32 m0, s48
	s_nop 0
	global_load_lds_dwordx4 v[162:163], off
	s_waitcnt vmcnt(8)
	s_waitcnt lgkmcnt(0)
	s_barrier
	s_waitcnt lgkmcnt(0)
	v_mfma_f32_16x16x32_bf16 v[60:63], v[140:143], v[188:191], v[60:63]
	v_mfma_f32_16x16x32_bf16 v[56:59], v[148:151], v[188:191], v[56:59]
	v_mfma_f32_16x16x32_bf16 v[44:47], v[140:143], v[196:199], v[44:47]
	v_mfma_f32_16x16x32_bf16 v[40:43], v[148:151], v[196:199], v[40:43]
	v_mfma_f32_16x16x32_bf16 v[28:31], v[140:143], v[204:207], v[28:31]
	v_mfma_f32_16x16x32_bf16 v[24:27], v[148:151], v[204:207], v[24:27]
	v_mfma_f32_16x16x32_bf16 v[12:15], v[140:143], v[212:215], v[12:15]
	v_mfma_f32_16x16x32_bf16 v[8:11], v[148:151], v[212:215], v[8:11]
	v_mfma_f32_16x16x32_bf16 v[60:63], v[144:147], v[192:195], v[60:63]
	v_mfma_f32_16x16x32_bf16 v[56:59], v[156:159], v[192:195], v[56:59]
	v_mfma_f32_16x16x32_bf16 v[44:47], v[144:147], v[200:203], v[44:47]
	v_mfma_f32_16x16x32_bf16 v[40:43], v[156:159], v[200:203], v[40:43]
	v_mfma_f32_16x16x32_bf16 v[28:31], v[144:147], v[208:211], v[28:31]
	v_mfma_f32_16x16x32_bf16 v[24:27], v[156:159], v[208:211], v[24:27]
	v_mfma_f32_16x16x32_bf16 v[12:15], v[144:147], v[216:219], v[12:15]
	v_mfma_f32_16x16x32_bf16 v[8:11], v[156:159], v[216:219], v[8:11]
	v_mfma_f32_16x16x32_bf16 v[52:55], v[172:175], v[188:191], v[52:55]
	v_mfma_f32_16x16x32_bf16 v[48:51], v[180:183], v[188:191], v[48:51]
	v_mfma_f32_16x16x32_bf16 v[36:39], v[172:175], v[196:199], v[36:39]
	v_mfma_f32_16x16x32_bf16 v[32:35], v[180:183], v[196:199], v[32:35]
	v_mfma_f32_16x16x32_bf16 v[20:23], v[172:175], v[204:207], v[20:23]
	v_mfma_f32_16x16x32_bf16 v[16:19], v[180:183], v[204:207], v[16:19]
	v_mfma_f32_16x16x32_bf16 v[4:7], v[172:175], v[212:215], v[4:7]
	v_mfma_f32_16x16x32_bf16 v[0:3], v[180:183], v[212:215], v[0:3]
	v_mfma_f32_16x16x32_bf16 v[52:55], v[176:179], v[192:195], v[52:55]
	v_mfma_f32_16x16x32_bf16 v[48:51], v[184:187], v[192:195], v[48:51]
	v_mfma_f32_16x16x32_bf16 v[36:39], v[176:179], v[200:203], v[36:39]
	v_mfma_f32_16x16x32_bf16 v[32:35], v[184:187], v[200:203], v[32:35]
	v_mfma_f32_16x16x32_bf16 v[20:23], v[176:179], v[208:211], v[20:23]
	v_mfma_f32_16x16x32_bf16 v[16:19], v[184:187], v[208:211], v[16:19]
	v_mfma_f32_16x16x32_bf16 v[4:7], v[176:179], v[216:219], v[4:7]
	v_mfma_f32_16x16x32_bf16 v[0:3], v[184:187], v[216:219], v[0:3]
	s_barrier
	s_add_i32 s52, s52, 2
	s_add_u32 s30, s30, 0x100
	s_addc_u32 s31, s31, 0
	s_add_u32 s24, s24, 0x100
	s_addc_u32 s25, s25, 0
	s_cmp_gt_u32 s52, 13
	s_cbranch_scc0 .LBB0_1162
	s_and_b64 vcc, exec, s[14:15]
	s_cbranch_vccz .LBB0_1165
	s_barrier

.LBB0_1716:
	s_add_u32 s30, s10, s28
	s_addc_u32 s31, s11, s29
	s_add_u32 s30, s30, 0x100
	s_addc_u32 s31, s31, 0
	s_add_u32 s40, s49, s28
	s_addc_u32 s41, s52, s29
	s_add_i32 s63, 0, 0x10000
	s_cmpk_eq_i32 s28, 0x700
	s_cselect_b32 s35, s15, s31
	s_cselect_b32 s34, s56, s30
	v_add_u32_e32 v147, s63, v143
	s_cselect_b32 s31, s13, s41
	s_cselect_b32 s30, s57, s40
	s_add_i32 s64, 0, 0x14000
	ds_read_b128 v[152:155], v147
	ds_read_b128 v[156:159], v147 offset:1024
	ds_read_b128 v[172:175], v147 offset:2048
	ds_read_b128 v[176:179], v147 offset:3072
	v_add_u32_e32 v147, s64, v143
	ds_read_b128 v[180:183], v147
	ds_read_b128 v[184:187], v147 offset:1024
	ds_read_b128 v[188:191], v147 offset:2048
	ds_read_b128 v[192:195], v147 offset:3072
	v_lshl_add_u64 v[148:149], v[140:141], 0, s[28:29]
	s_add_i32 m0, s4, 0xc000
	ds_read_b128 v[196:199], v146
	ds_read_b128 v[200:203], v146 offset:1024
	ds_read_b128 v[204:207], v146 offset:2048
	ds_read_b128 v[208:211], v146 offset:3072
	ds_read_b128 v[212:215], v146 offset:4096
	ds_read_b128 v[216:219], v146 offset:5120
	ds_read_b128 v[220:223], v146 offset:6144
	ds_read_b128 v[224:227], v146 offset:7168
	global_load_lds_dwordx4 v[148:149], off
	v_lshl_add_u64 v[148:149], v[138:139], 0, s[28:29]
	s_add_i32 m0, s4, 0xe000
	s_nop 0
	global_load_lds_dwordx4 v[148:149], off
	s_waitcnt vmcnt(8)
	s_waitcnt lgkmcnt(0)
	s_barrier
	s_waitcnt lgkmcnt(0)
	v_mfma_f32_16x16x32_bf16 v[52:55], v[152:155], v[196:199], v[52:55]
	v_mfma_f32_16x16x32_bf16 v[48:51], v[172:175], v[196:199], v[48:51]
	v_mfma_f32_16x16x32_bf16 v[72:75], v[152:155], v[204:207], v[72:75]
	v_mfma_f32_16x16x32_bf16 v[76:79], v[172:175], v[204:207], v[76:79]
	v_mfma_f32_16x16x32_bf16 v[104:107], v[152:155], v[212:215], v[104:107]
	v_mfma_f32_16x16x32_bf16 v[100:103], v[172:175], v[212:215], v[100:103]
	v_mfma_f32_16x16x32_bf16 v[124:127], v[152:155], v[220:223], v[124:127]
	v_mfma_f32_16x16x32_bf16 v[120:123], v[172:175], v[220:223], v[120:123]
	v_mfma_f32_16x16x32_bf16 v[52:55], v[156:159], v[200:203], v[52:55]
	v_mfma_f32_16x16x32_bf16 v[48:51], v[176:179], v[200:203], v[48:51]
	v_mfma_f32_16x16x32_bf16 v[72:75], v[156:159], v[208:211], v[72:75]
	v_mfma_f32_16x16x32_bf16 v[76:79], v[176:179], v[208:211], v[76:79]
	v_mfma_f32_16x16x32_bf16 v[104:107], v[156:159], v[216:219], v[104:107]
	v_mfma_f32_16x16x32_bf16 v[100:103], v[176:179], v[216:219], v[100:103]
	v_mfma_f32_16x16x32_bf16 v[124:127], v[156:159], v[224:227], v[124:127]
	v_mfma_f32_16x16x32_bf16 v[120:123], v[176:179], v[224:227], v[120:123]
	v_mfma_f32_16x16x32_bf16 v[60:63], v[180:183], v[196:199], v[60:63]
	v_mfma_f32_16x16x32_bf16 v[56:59], v[188:191], v[196:199], v[56:59]
	v_mfma_f32_16x16x32_bf16 v[88:91], v[180:183], v[204:207], v[88:91]
	v_mfma_f32_16x16x32_bf16 v[92:95], v[188:191], v[204:207], v[92:95]
	v_mfma_f32_16x16x32_bf16 v[116:119], v[180:183], v[212:215], v[116:119]
	v_mfma_f32_16x16x32_bf16 v[112:115], v[188:191], v[212:215], v[112:115]
	v_mfma_f32_16x16x32_bf16 v[108:111], v[180:183], v[220:223], v[108:111]
	v_mfma_f32_16x16x32_bf16 v[96:99], v[188:191], v[220:223], v[96:99]
	v_mfma_f32_16x16x32_bf16 v[60:63], v[184:187], v[200:203], v[60:63]
	v_mfma_f32_16x16x32_bf16 v[56:59], v[192:195], v[200:203], v[56:59]
	v_mfma_f32_16x16x32_bf16 v[88:91], v[184:187], v[208:211], v[88:91]
	v_mfma_f32_16x16x32_bf16 v[92:95], v[192:195], v[208:211], v[92:95]
	v_mfma_f32_16x16x32_bf16 v[116:119], v[184:187], v[216:219], v[116:119]
	v_mfma_f32_16x16x32_bf16 v[112:115], v[192:195], v[216:219], v[112:115]
	v_mfma_f32_16x16x32_bf16 v[108:111], v[184:187], v[224:227], v[108:111]
	v_mfma_f32_16x16x32_bf16 v[96:99], v[192:195], v[224:227], v[96:99]
	s_barrier
	s_add_i32 s40, s63, s3
	v_lshl_add_u64 v[148:149], s[30:31], 0, v[160:161]
	s_mov_b32 m0, s40
	ds_read_b128 v[196:199], v146 offset:16384
	ds_read_b128 v[200:203], v146 offset:17408
	ds_read_b128 v[204:207], v146 offset:18432
	ds_read_b128 v[208:211], v146 offset:19456
	ds_read_b128 v[212:215], v146 offset:20480
	ds_read_b128 v[216:219], v146 offset:21504
	ds_read_b128 v[220:223], v146 offset:22528
	ds_read_b128 v[224:227], v146 offset:23552
	global_load_lds_dwordx4 v[148:149], off
	s_add_i32 m0, s40, 0x2000
	s_add_u32 s40, s30, 0x40000
	v_lshl_add_u64 v[162:163], s[30:31], 0, v[128:129]
	s_addc_u32 s41, s31, 0
	s_add_i32 s63, s64, s3
	global_load_lds_dwordx4 v[162:163], off
	v_lshl_add_u64 v[164:165], s[40:41], 0, v[160:161]
	s_mov_b32 m0, s63
	v_lshl_add_u64 v[168:169], s[34:35], 0, v[130:131]
	global_load_lds_dwordx4 v[164:165], off
	v_lshl_add_u64 v[164:165], s[40:41], 0, v[128:129]
	s_add_i32 m0, s63, 0x2000
	s_nop 0
	global_load_lds_dwordx4 v[164:165], off
	v_lshl_add_u64 v[164:165], s[34:35], 0, v[132:133]
	s_mov_b32 m0, s4
	s_nop 0
	global_load_lds_dwordx4 v[164:165], off
	s_mov_b32 m0, s5
	s_nop 0
	global_load_lds_dwordx4 v[168:169], off
	s_waitcnt vmcnt(8)
	s_waitcnt lgkmcnt(0)
	s_barrier
	s_waitcnt lgkmcnt(0)
	v_mfma_f32_16x16x32_bf16 v[84:87], v[152:155], v[196:199], v[84:87]
	v_mfma_f32_16x16x32_bf16 v[80:83], v[172:175], v[196:199], v[80:83]
	v_mfma_f32_16x16x32_bf16 v[44:47], v[152:155], v[204:207], v[44:47]
	v_mfma_f32_16x16x32_bf16 v[40:43], v[172:175], v[204:207], v[40:43]
	v_mfma_f32_16x16x32_bf16 v[28:31], v[152:155], v[212:215], v[28:31]
	v_mfma_f32_16x16x32_bf16 v[24:27], v[172:175], v[212:215], v[24:27]
	v_mfma_f32_16x16x32_bf16 v[12:15], v[152:155], v[220:223], v[12:15]
	v_mfma_f32_16x16x32_bf16 v[8:11], v[172:175], v[220:223], v[8:11]
	v_mfma_f32_16x16x32_bf16 v[84:87], v[156:159], v[200:203], v[84:87]
	v_mfma_f32_16x16x32_bf16 v[80:83], v[176:179], v[200:203], v[80:83]
	v_mfma_f32_16x16x32_bf16 v[44:47], v[156:159], v[208:211], v[44:47]
	v_mfma_f32_16x16x32_bf16 v[40:43], v[176:179], v[208:211], v[40:43]
	v_mfma_f32_16x16x32_bf16 v[28:31], v[156:159], v[216:219], v[28:31]
	v_mfma_f32_16x16x32_bf16 v[24:27], v[176:179], v[216:219], v[24:27]
	v_mfma_f32_16x16x32_bf16 v[12:15], v[156:159], v[224:227], v[12:15]
	v_mfma_f32_16x16x32_bf16 v[8:11], v[176:179], v[224:227], v[8:11]
	v_mfma_f32_16x16x32_bf16 v[68:71], v[180:183], v[196:199], v[68:71]
	v_mfma_f32_16x16x32_bf16 v[64:67], v[188:191], v[196:199], v[64:67]
	v_mfma_f32_16x16x32_bf16 v[36:39], v[180:183], v[204:207], v[36:39]
	v_mfma_f32_16x16x32_bf16 v[32:35], v[188:191], v[204:207], v[32:35]
	v_mfma_f32_16x16x32_bf16 v[20:23], v[180:183], v[212:215], v[20:23]
	v_mfma_f32_16x16x32_bf16 v[16:19], v[188:191], v[212:215], v[16:19]
	v_mfma_f32_16x16x32_bf16 v[4:7], v[180:183], v[220:223], v[4:7]
	v_mfma_f32_16x16x32_bf16 v[0:3], v[188:191], v[220:223], v[0:3]
	v_mfma_f32_16x16x32_bf16 v[68:71], v[184:187], v[200:203], v[68:71]
	v_mfma_f32_16x16x32_bf16 v[64:67], v[192:195], v[200:203], v[64:67]
	v_mfma_f32_16x16x32_bf16 v[36:39], v[184:187], v[208:211], v[36:39]
	v_mfma_f32_16x16x32_bf16 v[32:35], v[192:195], v[208:211], v[32:35]
	v_mfma_f32_16x16x32_bf16 v[20:23], v[184:187], v[216:219], v[20:23]
	v_mfma_f32_16x16x32_bf16 v[16:19], v[192:195], v[216:219], v[16:19]
	v_mfma_f32_16x16x32_bf16 v[4:7], v[184:187], v[224:227], v[4:7]
	v_mfma_f32_16x16x32_bf16 v[0:3], v[192:195], v[224:227], v[0:3]
	s_barrier
	s_add_i32 s40, 0, 0x18000
	v_add_u32_e32 v147, s40, v143
	s_add_i32 s41, 0, 0x1c000
	ds_read_b128 v[152:155], v147
	ds_read_b128 v[156:159], v147 offset:1024
	ds_read_b128 v[172:175], v147 offset:2048
	ds_read_b128 v[176:179], v147 offset:3072
	v_add_u32_e32 v147, s41, v143
	ds_read_b128 v[180:183], v147
	ds_read_b128 v[184:187], v147 offset:1024
	ds_read_b128 v[188:191], v147 offset:2048
	ds_read_b128 v[192:195], v147 offset:3072
	s_add_u32 s34, s34, 0x40000
	s_addc_u32 s35, s35, 0
	s_mov_b32 m0, s23
	v_lshl_add_u64 v[170:171], s[34:35], 0, v[132:133]
	ds_read_b128 v[196:199], v146 offset:32768
	ds_read_b128 v[200:203], v146 offset:33792
	ds_read_b128 v[204:207], v146 offset:34816
	ds_read_b128 v[208:211], v146 offset:35840
	ds_read_b128 v[212:215], v146 offset:36864
	ds_read_b128 v[216:219], v146 offset:37888
	ds_read_b128 v[220:223], v146 offset:38912
	ds_read_b128 v[224:227], v146 offset:39936
	global_load_lds_dwordx4 v[170:171], off
	v_lshl_add_u64 v[170:171], s[34:35], 0, v[130:131]
	s_mov_b32 m0, s33
	s_nop 0
	global_load_lds_dwordx4 v[170:171], off
	s_waitcnt vmcnt(8)
	s_waitcnt lgkmcnt(0)
	s_barrier
	s_waitcnt lgkmcnt(0)
	v_mfma_f32_16x16x32_bf16 v[52:55], v[152:155], v[196:199], v[52:55]
	v_mfma_f32_16x16x32_bf16 v[48:51], v[172:175], v[196:199], v[48:51]
	v_mfma_f32_16x16x32_bf16 v[72:75], v[152:155], v[204:207], v[72:75]
	v_mfma_f32_16x16x32_bf16 v[76:79], v[172:175], v[204:207], v[76:79]
	v_mfma_f32_16x16x32_bf16 v[104:107], v[152:155], v[212:215], v[104:107]
	v_mfma_f32_16x16x32_bf16 v[100:103], v[172:175], v[212:215], v[100:103]
	v_mfma_f32_16x16x32_bf16 v[124:127], v[152:155], v[220:223], v[124:127]
	v_mfma_f32_16x16x32_bf16 v[120:123], v[172:175], v[220:223], v[120:123]
	v_mfma_f32_16x16x32_bf16 v[52:55], v[156:159], v[200:203], v[52:55]
	v_mfma_f32_16x16x32_bf16 v[48:51], v[176:179], v[200:203], v[48:51]
	v_mfma_f32_16x16x32_bf16 v[72:75], v[156:159], v[208:211], v[72:75]
	v_mfma_f32_16x16x32_bf16 v[76:79], v[176:179], v[208:211], v[76:79]
	v_mfma_f32_16x16x32_bf16 v[104:107], v[156:159], v[216:219], v[104:107]
	v_mfma_f32_16x16x32_bf16 v[100:103], v[176:179], v[216:219], v[100:103]
	v_mfma_f32_16x16x32_bf16 v[124:127], v[156:159], v[224:227], v[124:127]
	v_mfma_f32_16x16x32_bf16 v[120:123], v[176:179], v[224:227], v[120:123]
	v_mfma_f32_16x16x32_bf16 v[60:63], v[180:183], v[196:199], v[60:63]
	v_mfma_f32_16x16x32_bf16 v[56:59], v[188:191], v[196:199], v[56:59]
	v_mfma_f32_16x16x32_bf16 v[88:91], v[180:183], v[204:207], v[88:91]
	v_mfma_f32_16x16x32_bf16 v[92:95], v[188:191], v[204:207], v[92:95]
	v_mfma_f32_16x16x32_bf16 v[116:119], v[180:183], v[212:215], v[116:119]
	v_mfma_f32_16x16x32_bf16 v[112:115], v[188:191], v[212:215], v[112:115]
	v_mfma_f32_16x16x32_bf16 v[108:111], v[180:183], v[220:223], v[108:111]
	v_mfma_f32_16x16x32_bf16 v[96:99], v[188:191], v[220:223], v[96:99]
	v_mfma_f32_16x16x32_bf16 v[60:63], v[184:187], v[200:203], v[60:63]
	v_mfma_f32_16x16x32_bf16 v[56:59], v[192:195], v[200:203], v[56:59]
	v_mfma_f32_16x16x32_bf16 v[88:91], v[184:187], v[208:211], v[88:91]
	v_mfma_f32_16x16x32_bf16 v[92:95], v[192:195], v[208:211], v[92:95]
	v_mfma_f32_16x16x32_bf16 v[116:119], v[184:187], v[216:219], v[116:119]
	v_mfma_f32_16x16x32_bf16 v[112:115], v[192:195], v[216:219], v[112:115]
	v_mfma_f32_16x16x32_bf16 v[108:111], v[184:187], v[224:227], v[108:111]
	v_mfma_f32_16x16x32_bf16 v[96:99], v[192:195], v[224:227], v[96:99]
	s_barrier
	s_add_i32 s34, s40, s3
	v_lshl_add_u64 v[148:149], v[148:149], 0, s[50:51]
	s_mov_b32 m0, s34
	ds_read_b128 v[196:199], v146 offset:49152
	ds_read_b128 v[200:203], v146 offset:50176
	ds_read_b128 v[204:207], v146 offset:51200
	ds_read_b128 v[208:211], v146 offset:52224
	ds_read_b128 v[212:215], v146 offset:53248
	ds_read_b128 v[216:219], v146 offset:54272
	ds_read_b128 v[220:223], v146 offset:55296
	ds_read_b128 v[224:227], v146 offset:56320
	global_load_lds_dwordx4 v[148:149], off
	s_add_i32 m0, s34, 0x2000
	s_add_u32 s30, s30, 0x40080
	v_lshl_add_u64 v[148:149], v[162:163], 0, s[50:51]
	s_addc_u32 s31, s31, 0
	s_add_i32 s34, s41, s3
	global_load_lds_dwordx4 v[148:149], off
	v_lshl_add_u64 v[148:149], s[30:31], 0, v[160:161]
	s_mov_b32 m0, s34
	s_nop 0
	global_load_lds_dwordx4 v[148:149], off
	v_lshl_add_u64 v[148:149], s[30:31], 0, v[128:129]
	s_add_i32 m0, s34, 0x2000
	s_nop 0
	global_load_lds_dwordx4 v[148:149], off
	v_lshl_add_u64 v[148:149], v[164:165], 0, s[50:51]
	s_mov_b32 m0, s44
	s_nop 0
	global_load_lds_dwordx4 v[148:149], off
	v_lshl_add_u64 v[148:149], v[168:169], 0, s[50:51]
	s_mov_b32 m0, s46
	s_nop 0
	global_load_lds_dwordx4 v[148:149], off
	s_waitcnt vmcnt(8)
	s_waitcnt lgkmcnt(0)
	s_barrier
	s_waitcnt lgkmcnt(0)
	v_mfma_f32_16x16x32_bf16 v[84:87], v[152:155], v[196:199], v[84:87]
	v_mfma_f32_16x16x32_bf16 v[80:83], v[172:175], v[196:199], v[80:83]
	v_mfma_f32_16x16x32_bf16 v[44:47], v[152:155], v[204:207], v[44:47]
	v_mfma_f32_16x16x32_bf16 v[40:43], v[172:175], v[204:207], v[40:43]
	v_mfma_f32_16x16x32_bf16 v[28:31], v[152:155], v[212:215], v[28:31]
	v_mfma_f32_16x16x32_bf16 v[24:27], v[172:175], v[212:215], v[24:27]
	v_mfma_f32_16x16x32_bf16 v[12:15], v[152:155], v[220:223], v[12:15]
	v_mfma_f32_16x16x32_bf16 v[8:11], v[172:175], v[220:223], v[8:11]
	v_mfma_f32_16x16x32_bf16 v[84:87], v[156:159], v[200:203], v[84:87]
	v_mfma_f32_16x16x32_bf16 v[80:83], v[176:179], v[200:203], v[80:83]
	v_mfma_f32_16x16x32_bf16 v[44:47], v[156:159], v[208:211], v[44:47]
	v_mfma_f32_16x16x32_bf16 v[40:43], v[176:179], v[208:211], v[40:43]
	v_mfma_f32_16x16x32_bf16 v[28:31], v[156:159], v[216:219], v[28:31]
	v_mfma_f32_16x16x32_bf16 v[24:27], v[176:179], v[216:219], v[24:27]
	v_mfma_f32_16x16x32_bf16 v[12:15], v[156:159], v[224:227], v[12:15]
	v_mfma_f32_16x16x32_bf16 v[8:11], v[176:179], v[224:227], v[8:11]
	v_mfma_f32_16x16x32_bf16 v[68:71], v[180:183], v[196:199], v[68:71]
	v_mfma_f32_16x16x32_bf16 v[64:67], v[188:191], v[196:199], v[64:67]
	v_mfma_f32_16x16x32_bf16 v[36:39], v[180:183], v[204:207], v[36:39]
	v_mfma_f32_16x16x32_bf16 v[32:35], v[188:191], v[204:207], v[32:35]
	v_mfma_f32_16x16x32_bf16 v[20:23], v[180:183], v[212:215], v[20:23]
	v_mfma_f32_16x16x32_bf16 v[16:19], v[188:191], v[212:215], v[16:19]
	v_mfma_f32_16x16x32_bf16 v[4:7], v[180:183], v[220:223], v[4:7]
	v_mfma_f32_16x16x32_bf16 v[0:3], v[188:191], v[220:223], v[0:3]
	v_mfma_f32_16x16x32_bf16 v[68:71], v[184:187], v[200:203], v[68:71]
	v_mfma_f32_16x16x32_bf16 v[64:67], v[192:195], v[200:203], v[64:67]
	v_mfma_f32_16x16x32_bf16 v[36:39], v[184:187], v[208:211], v[36:39]
	v_mfma_f32_16x16x32_bf16 v[32:35], v[192:195], v[208:211], v[32:35]
	v_mfma_f32_16x16x32_bf16 v[20:23], v[184:187], v[216:219], v[20:23]
	v_mfma_f32_16x16x32_bf16 v[16:19], v[192:195], v[216:219], v[16:19]
	v_mfma_f32_16x16x32_bf16 v[4:7], v[184:187], v[224:227], v[4:7]
	v_mfma_f32_16x16x32_bf16 v[0:3], v[192:195], v[224:227], v[0:3]
	s_barrier
	s_add_i32 s62, s62, 2
	s_add_u32 s28, s28, 0x100
	s_addc_u32 s29, s29, 0
	s_cmp_gt_u32 s62, 13
	s_cbranch_scc0 .LBB0_1716
	s_add_u32 s28, s49, 0xffffff00
	s_addc_u32 s29, s52, -1
	s_andn2_b64 vcc, exec, s[8:9]
	s_cbranch_vccnz .LBB0_1719
	v_mov_b32_e32 v0, 0
	s_mov_b32 s22, s12
	s_mov_b32 s20, s14
	s_mov_b64 s[10:11], s[26:27]
	s_mov_b32 s47, s48
	v_mov_b32_e32 v1, v0
	v_mov_b32_e32 v2, v0
	v_mov_b32_e32 v3, v0
	v_mov_b32_e32 v4, v0
	v_mov_b32_e32 v5, v0
	v_mov_b32_e32 v6, v0
	v_mov_b32_e32 v7, v0
	v_mov_b32_e32 v16, v0
	v_mov_b32_e32 v17, v0
	v_mov_b32_e32 v18, v0
	v_mov_b32_e32 v19, v0
	v_mov_b32_e32 v20, v0
	v_mov_b32_e32 v21, v0
	v_mov_b32_e32 v22, v0
	v_mov_b32_e32 v23, v0
	v_mov_b32_e32 v32, v0
	v_mov_b32_e32 v33, v0
	v_mov_b32_e32 v34, v0
	v_mov_b32_e32 v35, v0
	v_mov_b32_e32 v36, v0
	v_mov_b32_e32 v37, v0
	v_mov_b32_e32 v38, v0
	v_mov_b32_e32 v39, v0
	v_mov_b32_e32 v64, v0
	v_mov_b32_e32 v65, v0
	v_mov_b32_e32 v66, v0
	v_mov_b32_e32 v67, v0
	v_mov_b32_e32 v68, v0
	v_mov_b32_e32 v69, v0
	v_mov_b32_e32 v70, v0
	v_mov_b32_e32 v71, v0
	v_mov_b32_e32 v8, v0
	v_mov_b32_e32 v9, v0
	v_mov_b32_e32 v10, v0
	v_mov_b32_e32 v11, v0
	v_mov_b32_e32 v12, v0
	v_mov_b32_e32 v13, v0
	v_mov_b32_e32 v14, v0
	v_mov_b32_e32 v15, v0
	v_mov_b32_e32 v24, v0
	v_mov_b32_e32 v25, v0
	v_mov_b32_e32 v26, v0
	v_mov_b32_e32 v27, v0
	v_mov_b32_e32 v28, v0
	v_mov_b32_e32 v29, v0
	v_mov_b32_e32 v30, v0
	v_mov_b32_e32 v31, v0
	v_mov_b32_e32 v40, v0
	v_mov_b32_e32 v41, v0
	v_mov_b32_e32 v42, v0
	v_mov_b32_e32 v43, v0
	v_mov_b32_e32 v44, v0
	v_mov_b32_e32 v45, v0
	v_mov_b32_e32 v46, v0
	v_mov_b32_e32 v47, v0
	v_mov_b32_e32 v80, v0
	v_mov_b32_e32 v81, v0
	v_mov_b32_e32 v82, v0
	v_mov_b32_e32 v83, v0
	v_mov_b32_e32 v84, v0
	v_mov_b32_e32 v85, v0
	v_mov_b32_e32 v86, v0
	v_mov_b32_e32 v87, v0
	v_mov_b32_e32 v96, v0
	v_mov_b32_e32 v97, v0
	v_mov_b32_e32 v98, v0
	v_mov_b32_e32 v99, v0
	v_mov_b32_e32 v108, v0
	v_mov_b32_e32 v109, v0
	v_mov_b32_e32 v110, v0
	v_mov_b32_e32 v111, v0
	v_mov_b32_e32 v112, v0
	v_mov_b32_e32 v113, v0
	v_mov_b32_e32 v114, v0
	v_mov_b32_e32 v115, v0
	v_mov_b32_e32 v116, v0
	v_mov_b32_e32 v117, v0
	v_mov_b32_e32 v118, v0
	v_mov_b32_e32 v119, v0
	v_mov_b32_e32 v92, v0
	v_mov_b32_e32 v93, v0
	v_mov_b32_e32 v94, v0
	v_mov_b32_e32 v95, v0
	v_mov_b32_e32 v88, v0
	v_mov_b32_e32 v89, v0
	v_mov_b32_e32 v90, v0
	v_mov_b32_e32 v91, v0
	v_mov_b32_e32 v56, v0
	v_mov_b32_e32 v57, v0
	v_mov_b32_e32 v58, v0
	v_mov_b32_e32 v59, v0
	v_mov_b32_e32 v60, v0
	v_mov_b32_e32 v61, v0
	v_mov_b32_e32 v62, v0
	v_mov_b32_e32 v63, v0
	v_mov_b32_e32 v120, v0
	v_mov_b32_e32 v121, v0
	v_mov_b32_e32 v122, v0
	v_mov_b32_e32 v123, v0
	v_mov_b32_e32 v124, v0
	v_mov_b32_e32 v125, v0
	v_mov_b32_e32 v126, v0
	v_mov_b32_e32 v127, v0
	v_mov_b32_e32 v100, v0
	v_mov_b32_e32 v101, v0
	v_mov_b32_e32 v102, v0
	v_mov_b32_e32 v103, v0
	v_mov_b32_e32 v104, v0
	v_mov_b32_e32 v105, v0
	v_mov_b32_e32 v106, v0
	v_mov_b32_e32 v107, v0
	v_mov_b32_e32 v76, v0
	v_mov_b32_e32 v77, v0
	v_mov_b32_e32 v78, v0
	v_mov_b32_e32 v79, v0
	v_mov_b32_e32 v72, v0
	v_mov_b32_e32 v73, v0
	v_mov_b32_e32 v74, v0
	v_mov_b32_e32 v75, v0
	v_mov_b32_e32 v48, v0
	v_mov_b32_e32 v49, v0
	v_mov_b32_e32 v50, v0
	v_mov_b32_e32 v51, v0
	v_mov_b32_e32 v52, v0
	v_mov_b32_e32 v53, v0
	v_mov_b32_e32 v54, v0
	v_mov_b32_e32 v55, v0
	s_andn2_b64 vcc, exec, s[6:7]
	s_cbranch_vccnz .LBB0_1720
	s_branch .LBB0_1721

.LBB0_1916:
	s_lshl_b32 s84, s92, 7
	s_add_u32 s85, s74, s84
	s_addc_u32 vcc_lo, s75, 0
	s_add_u32 s82, s85, 0x100
	s_addc_u32 s83, vcc_lo, 0
	s_and_b64 s[40:41], s[80:81], exec
	s_cselect_b32 s83, s17, s83
	s_cselect_b32 s82, s67, s82
	s_add_u32 s40, s76, s84
	s_addc_u32 s41, s77, 0
	s_add_u32 s84, s40, 0x100
	s_addc_u32 vcc_hi, s41, 0
	s_and_b64 s[40:41], s[80:81], exec
	s_cselect_b32 s81, s65, vcc_hi
	s_cselect_b32 s80, s73, s84
	s_add_i32 s84, 0, 0x10000
	s_add_i32 vcc_hi, 0, 0x14000
	v_add_u32_e32 v140, s84, v238
	v_add_u32_e32 v156, vcc_hi, v238
	ds_read_b128 v[128:131], v140
	ds_read_b128 v[132:135], v140 offset:1024
	ds_read_b128 v[136:139], v140 offset:2048
	ds_read_b128 v[140:143], v140 offset:3072
	ds_read_b128 v[144:147], v156
	ds_read_b128 v[148:151], v156 offset:1024
	ds_read_b128 v[152:155], v156 offset:2048
	ds_read_b128 v[156:159], v156 offset:3072
	s_add_u32 s40, s85, 0x40080
	s_addc_u32 s41, vcc_lo, 0
	v_lshl_add_u64 v[162:163], s[40:41], 0, v[172:173]
	s_add_i32 m0, s46, 0xc000
	ds_read_b128 v[186:189], v252
	ds_read_b128 v[190:193], v252 offset:1024
	ds_read_b128 v[194:197], v252 offset:2048
	ds_read_b128 v[198:201], v252 offset:3072
	ds_read_b128 v[202:205], v252 offset:4096
	ds_read_b128 v[206:209], v252 offset:5120
	ds_read_b128 v[210:213], v252 offset:6144
	ds_read_b128 v[214:217], v252 offset:7168
	global_load_lds_dwordx4 v[162:163], off
	v_lshl_add_u64 v[162:163], s[40:41], 0, v[176:177]
	s_add_i32 m0, s46, 0xe000
	s_nop 0
	global_load_lds_dwordx4 v[162:163], off
	s_waitcnt vmcnt(8)
	s_waitcnt lgkmcnt(0)
	s_barrier
	s_waitcnt lgkmcnt(0)
	v_mfma_f32_16x16x32_bf16 v[124:127], v[128:131], v[186:189], v[124:127]
	v_mfma_f32_16x16x32_bf16 v[120:123], v[136:139], v[186:189], v[120:123]
	v_mfma_f32_16x16x32_bf16 v[108:111], v[128:131], v[194:197], v[108:111]
	v_mfma_f32_16x16x32_bf16 v[104:107], v[136:139], v[194:197], v[104:107]
	v_mfma_f32_16x16x32_bf16 v[92:95], v[128:131], v[202:205], v[92:95]
	v_mfma_f32_16x16x32_bf16 v[88:91], v[136:139], v[202:205], v[88:91]
	v_mfma_f32_16x16x32_bf16 v[76:79], v[128:131], v[210:213], v[76:79]
	v_mfma_f32_16x16x32_bf16 v[72:75], v[136:139], v[210:213], v[72:75]
	v_mfma_f32_16x16x32_bf16 v[124:127], v[132:135], v[190:193], v[124:127]
	v_mfma_f32_16x16x32_bf16 v[120:123], v[140:143], v[190:193], v[120:123]
	v_mfma_f32_16x16x32_bf16 v[108:111], v[132:135], v[198:201], v[108:111]
	v_mfma_f32_16x16x32_bf16 v[104:107], v[140:143], v[198:201], v[104:107]
	v_mfma_f32_16x16x32_bf16 v[92:95], v[132:135], v[206:209], v[92:95]
	v_mfma_f32_16x16x32_bf16 v[88:91], v[140:143], v[206:209], v[88:91]
	v_mfma_f32_16x16x32_bf16 v[76:79], v[132:135], v[214:217], v[76:79]
	v_mfma_f32_16x16x32_bf16 v[72:75], v[140:143], v[214:217], v[72:75]
	v_mfma_f32_16x16x32_bf16 v[116:119], v[144:147], v[186:189], v[116:119]
	v_mfma_f32_16x16x32_bf16 v[112:115], v[152:155], v[186:189], v[112:115]
	v_mfma_f32_16x16x32_bf16 v[100:103], v[144:147], v[194:197], v[100:103]
	v_mfma_f32_16x16x32_bf16 v[96:99], v[152:155], v[194:197], v[96:99]
	v_mfma_f32_16x16x32_bf16 v[84:87], v[144:147], v[202:205], v[84:87]
	v_mfma_f32_16x16x32_bf16 v[80:83], v[152:155], v[202:205], v[80:83]
	v_mfma_f32_16x16x32_bf16 v[68:71], v[144:147], v[210:213], v[68:71]
	v_mfma_f32_16x16x32_bf16 v[64:67], v[152:155], v[210:213], v[64:67]
	v_mfma_f32_16x16x32_bf16 v[116:119], v[148:151], v[190:193], v[116:119]
	v_mfma_f32_16x16x32_bf16 v[112:115], v[156:159], v[190:193], v[112:115]
	v_mfma_f32_16x16x32_bf16 v[100:103], v[148:151], v[198:201], v[100:103]
	v_mfma_f32_16x16x32_bf16 v[96:99], v[156:159], v[198:201], v[96:99]
	v_mfma_f32_16x16x32_bf16 v[84:87], v[148:151], v[206:209], v[84:87]
	v_mfma_f32_16x16x32_bf16 v[80:83], v[156:159], v[206:209], v[80:83]
	v_mfma_f32_16x16x32_bf16 v[68:71], v[148:151], v[214:217], v[68:71]
	v_mfma_f32_16x16x32_bf16 v[64:67], v[156:159], v[214:217], v[64:67]
	s_barrier
	s_add_i32 s40, s84, s52
	v_lshl_add_u64 v[162:163], s[80:81], 0, v[174:175]
	s_mov_b32 m0, s40
	ds_read_b128 v[186:189], v252 offset:16384
	ds_read_b128 v[190:193], v252 offset:17408
	ds_read_b128 v[194:197], v252 offset:18432
	ds_read_b128 v[198:201], v252 offset:19456
	ds_read_b128 v[202:205], v252 offset:20480
	ds_read_b128 v[206:209], v252 offset:21504
	ds_read_b128 v[210:213], v252 offset:22528
	ds_read_b128 v[214:217], v252 offset:23552
	global_load_lds_dwordx4 v[162:163], off
	s_add_i32 m0, s40, 0x2000
	s_add_u32 s40, s80, 0x40000
	v_lshl_add_u64 v[164:165], s[80:81], 0, v[178:179]
	s_addc_u32 s41, s81, 0
	s_add_i32 s84, vcc_hi, s52
	global_load_lds_dwordx4 v[164:165], off
	v_lshl_add_u64 v[168:169], s[40:41], 0, v[174:175]
	s_mov_b32 m0, s84
	v_lshl_add_u64 v[170:171], s[82:83], 0, v[176:177]
	global_load_lds_dwordx4 v[168:169], off
	v_lshl_add_u64 v[168:169], s[40:41], 0, v[178:179]
	s_add_i32 m0, s84, 0x2000
	s_nop 0
	global_load_lds_dwordx4 v[168:169], off
	v_lshl_add_u64 v[168:169], s[82:83], 0, v[172:173]
	s_mov_b32 m0, s46
	s_nop 0
	global_load_lds_dwordx4 v[168:169], off
	s_mov_b32 m0, s47
	s_nop 0
	global_load_lds_dwordx4 v[170:171], off
	s_waitcnt vmcnt(8)
	s_waitcnt lgkmcnt(0)
	s_barrier
	s_waitcnt lgkmcnt(0)
	v_mfma_f32_16x16x32_bf16 v[60:63], v[128:131], v[186:189], v[60:63]
	v_mfma_f32_16x16x32_bf16 v[56:59], v[136:139], v[186:189], v[56:59]
	v_mfma_f32_16x16x32_bf16 v[44:47], v[128:131], v[194:197], v[44:47]
	v_mfma_f32_16x16x32_bf16 v[40:43], v[136:139], v[194:197], v[40:43]
	v_mfma_f32_16x16x32_bf16 v[28:31], v[128:131], v[202:205], v[28:31]
	v_mfma_f32_16x16x32_bf16 v[24:27], v[136:139], v[202:205], v[24:27]
	v_mfma_f32_16x16x32_bf16 v[12:15], v[128:131], v[210:213], v[12:15]
	v_mfma_f32_16x16x32_bf16 v[8:11], v[136:139], v[210:213], v[8:11]
	v_mfma_f32_16x16x32_bf16 v[60:63], v[132:135], v[190:193], v[60:63]
	v_mfma_f32_16x16x32_bf16 v[56:59], v[140:143], v[190:193], v[56:59]
	v_mfma_f32_16x16x32_bf16 v[44:47], v[132:135], v[198:201], v[44:47]
	v_mfma_f32_16x16x32_bf16 v[40:43], v[140:143], v[198:201], v[40:43]
	v_mfma_f32_16x16x32_bf16 v[28:31], v[132:135], v[206:209], v[28:31]
	v_mfma_f32_16x16x32_bf16 v[24:27], v[140:143], v[206:209], v[24:27]
	v_mfma_f32_16x16x32_bf16 v[12:15], v[132:135], v[214:217], v[12:15]
	v_mfma_f32_16x16x32_bf16 v[8:11], v[140:143], v[214:217], v[8:11]
	v_mfma_f32_16x16x32_bf16 v[52:55], v[144:147], v[186:189], v[52:55]
	v_mfma_f32_16x16x32_bf16 v[48:51], v[152:155], v[186:189], v[48:51]
	v_mfma_f32_16x16x32_bf16 v[36:39], v[144:147], v[194:197], v[36:39]
	v_mfma_f32_16x16x32_bf16 v[32:35], v[152:155], v[194:197], v[32:35]
	v_mfma_f32_16x16x32_bf16 v[20:23], v[144:147], v[202:205], v[20:23]
	v_mfma_f32_16x16x32_bf16 v[16:19], v[152:155], v[202:205], v[16:19]
	v_mfma_f32_16x16x32_bf16 v[4:7], v[144:147], v[210:213], v[4:7]
	v_mfma_f32_16x16x32_bf16 v[0:3], v[152:155], v[210:213], v[0:3]
	v_mfma_f32_16x16x32_bf16 v[52:55], v[148:151], v[190:193], v[52:55]
	v_mfma_f32_16x16x32_bf16 v[48:51], v[156:159], v[190:193], v[48:51]
	v_mfma_f32_16x16x32_bf16 v[36:39], v[148:151], v[198:201], v[36:39]
	v_mfma_f32_16x16x32_bf16 v[32:35], v[156:159], v[198:201], v[32:35]
	v_mfma_f32_16x16x32_bf16 v[20:23], v[148:151], v[206:209], v[20:23]
	v_mfma_f32_16x16x32_bf16 v[16:19], v[156:159], v[206:209], v[16:19]
	v_mfma_f32_16x16x32_bf16 v[4:7], v[148:151], v[214:217], v[4:7]
	v_mfma_f32_16x16x32_bf16 v[0:3], v[156:159], v[214:217], v[0:3]
	s_barrier
	s_add_i32 s84, 0, 0x18000
	s_add_i32 s85, 0, 0x1c000
	v_add_u32_e32 v140, s84, v238
	v_add_u32_e32 v156, s85, v238
	ds_read_b128 v[128:131], v140
	ds_read_b128 v[132:135], v140 offset:1024
	ds_read_b128 v[136:139], v140 offset:2048
	ds_read_b128 v[140:143], v140 offset:3072
	ds_read_b128 v[144:147], v156
	ds_read_b128 v[148:151], v156 offset:1024
	ds_read_b128 v[152:155], v156 offset:2048
	ds_read_b128 v[156:159], v156 offset:3072
	s_add_u32 s40, s82, 0x40000
	s_addc_u32 s41, s83, 0
	s_mov_b32 m0, s48
	v_lshl_add_u64 v[218:219], s[40:41], 0, v[172:173]
	ds_read_b128 v[186:189], v252 offset:32768
	ds_read_b128 v[190:193], v252 offset:33792
	ds_read_b128 v[194:197], v252 offset:34816
	ds_read_b128 v[198:201], v252 offset:35840
	ds_read_b128 v[202:205], v252 offset:36864
	ds_read_b128 v[206:209], v252 offset:37888
	ds_read_b128 v[210:213], v252 offset:38912
	ds_read_b128 v[214:217], v252 offset:39936
	global_load_lds_dwordx4 v[218:219], off
	v_lshl_add_u64 v[218:219], s[40:41], 0, v[176:177]
	s_mov_b32 m0, s49
	s_nop 0
	global_load_lds_dwordx4 v[218:219], off
	s_waitcnt vmcnt(8)
	s_waitcnt lgkmcnt(0)
	s_barrier
	s_waitcnt lgkmcnt(0)
	v_mfma_f32_16x16x32_bf16 v[124:127], v[128:131], v[186:189], v[124:127]
	v_mfma_f32_16x16x32_bf16 v[120:123], v[136:139], v[186:189], v[120:123]
	v_mfma_f32_16x16x32_bf16 v[108:111], v[128:131], v[194:197], v[108:111]
	v_mfma_f32_16x16x32_bf16 v[104:107], v[136:139], v[194:197], v[104:107]
	v_mfma_f32_16x16x32_bf16 v[92:95], v[128:131], v[202:205], v[92:95]
	v_mfma_f32_16x16x32_bf16 v[88:91], v[136:139], v[202:205], v[88:91]
	v_mfma_f32_16x16x32_bf16 v[76:79], v[128:131], v[210:213], v[76:79]
	v_mfma_f32_16x16x32_bf16 v[72:75], v[136:139], v[210:213], v[72:75]
	v_mfma_f32_16x16x32_bf16 v[124:127], v[132:135], v[190:193], v[124:127]
	v_mfma_f32_16x16x32_bf16 v[120:123], v[140:143], v[190:193], v[120:123]
	v_mfma_f32_16x16x32_bf16 v[108:111], v[132:135], v[198:201], v[108:111]
	v_mfma_f32_16x16x32_bf16 v[104:107], v[140:143], v[198:201], v[104:107]
	v_mfma_f32_16x16x32_bf16 v[92:95], v[132:135], v[206:209], v[92:95]
	v_mfma_f32_16x16x32_bf16 v[88:91], v[140:143], v[206:209], v[88:91]
	v_mfma_f32_16x16x32_bf16 v[76:79], v[132:135], v[214:217], v[76:79]
	v_mfma_f32_16x16x32_bf16 v[72:75], v[140:143], v[214:217], v[72:75]
	v_mfma_f32_16x16x32_bf16 v[116:119], v[144:147], v[186:189], v[116:119]
	v_mfma_f32_16x16x32_bf16 v[112:115], v[152:155], v[186:189], v[112:115]
	v_mfma_f32_16x16x32_bf16 v[100:103], v[144:147], v[194:197], v[100:103]
	v_mfma_f32_16x16x32_bf16 v[96:99], v[152:155], v[194:197], v[96:99]
	v_mfma_f32_16x16x32_bf16 v[84:87], v[144:147], v[202:205], v[84:87]
	v_mfma_f32_16x16x32_bf16 v[80:83], v[152:155], v[202:205], v[80:83]
	v_mfma_f32_16x16x32_bf16 v[68:71], v[144:147], v[210:213], v[68:71]
	v_mfma_f32_16x16x32_bf16 v[64:67], v[152:155], v[210:213], v[64:67]
	v_mfma_f32_16x16x32_bf16 v[116:119], v[148:151], v[190:193], v[116:119]
	v_mfma_f32_16x16x32_bf16 v[112:115], v[156:159], v[190:193], v[112:115]
	v_mfma_f32_16x16x32_bf16 v[100:103], v[148:151], v[198:201], v[100:103]
	v_mfma_f32_16x16x32_bf16 v[96:99], v[156:159], v[198:201], v[96:99]
	v_mfma_f32_16x16x32_bf16 v[84:87], v[148:151], v[206:209], v[84:87]
	v_mfma_f32_16x16x32_bf16 v[80:83], v[156:159], v[206:209], v[80:83]
	v_mfma_f32_16x16x32_bf16 v[68:71], v[148:151], v[214:217], v[68:71]
	v_mfma_f32_16x16x32_bf16 v[64:67], v[156:159], v[214:217], v[64:67]
	s_barrier
	s_add_i32 s40, s84, s52
	v_lshl_add_u64 v[162:163], v[162:163], 0, s[50:51]
	s_mov_b32 m0, s40
	ds_read_b128 v[186:189], v252 offset:49152
	ds_read_b128 v[190:193], v252 offset:50176
	ds_read_b128 v[194:197], v252 offset:51200
	ds_read_b128 v[198:201], v252 offset:52224
	ds_read_b128 v[202:205], v252 offset:53248
	ds_read_b128 v[206:209], v252 offset:54272
	ds_read_b128 v[210:213], v252 offset:55296
	ds_read_b128 v[214:217], v252 offset:56320
	global_load_lds_dwordx4 v[162:163], off
	s_add_i32 m0, s40, 0x2000
	s_add_u32 s40, s80, 0x40080
	v_lshl_add_u64 v[162:163], v[164:165], 0, s[50:51]
	s_addc_u32 s41, s81, 0
	s_add_i32 s80, s85, s52
	global_load_lds_dwordx4 v[162:163], off
	v_lshl_add_u64 v[162:163], s[40:41], 0, v[174:175]
	s_mov_b32 m0, s80
	s_nop 0
	global_load_lds_dwordx4 v[162:163], off
	v_lshl_add_u64 v[162:163], s[40:41], 0, v[178:179]
	s_add_i32 m0, s80, 0x2000
	s_nop 0
	global_load_lds_dwordx4 v[162:163], off
	v_lshl_add_u64 v[162:163], v[168:169], 0, s[50:51]
	s_mov_b32 m0, s3
	s_nop 0
	global_load_lds_dwordx4 v[162:163], off
	v_lshl_add_u64 v[162:163], v[170:171], 0, s[50:51]
	s_mov_b32 m0, s86
	s_nop 0
	global_load_lds_dwordx4 v[162:163], off
	s_waitcnt vmcnt(8)
	s_waitcnt lgkmcnt(0)
	s_barrier
	s_waitcnt lgkmcnt(0)
	v_mfma_f32_16x16x32_bf16 v[60:63], v[128:131], v[186:189], v[60:63]
	v_mfma_f32_16x16x32_bf16 v[56:59], v[136:139], v[186:189], v[56:59]
	v_mfma_f32_16x16x32_bf16 v[44:47], v[128:131], v[194:197], v[44:47]
	v_mfma_f32_16x16x32_bf16 v[40:43], v[136:139], v[194:197], v[40:43]
	v_mfma_f32_16x16x32_bf16 v[28:31], v[128:131], v[202:205], v[28:31]
	v_mfma_f32_16x16x32_bf16 v[24:27], v[136:139], v[202:205], v[24:27]
	v_mfma_f32_16x16x32_bf16 v[12:15], v[128:131], v[210:213], v[12:15]
	v_mfma_f32_16x16x32_bf16 v[8:11], v[136:139], v[210:213], v[8:11]
	v_mfma_f32_16x16x32_bf16 v[60:63], v[132:135], v[190:193], v[60:63]
	v_mfma_f32_16x16x32_bf16 v[56:59], v[140:143], v[190:193], v[56:59]
	v_mfma_f32_16x16x32_bf16 v[44:47], v[132:135], v[198:201], v[44:47]
	v_mfma_f32_16x16x32_bf16 v[40:43], v[140:143], v[198:201], v[40:43]
	v_mfma_f32_16x16x32_bf16 v[28:31], v[132:135], v[206:209], v[28:31]
	v_mfma_f32_16x16x32_bf16 v[24:27], v[140:143], v[206:209], v[24:27]
	v_mfma_f32_16x16x32_bf16 v[12:15], v[132:135], v[214:217], v[12:15]
	v_mfma_f32_16x16x32_bf16 v[8:11], v[140:143], v[214:217], v[8:11]
	v_mfma_f32_16x16x32_bf16 v[52:55], v[144:147], v[186:189], v[52:55]
	v_mfma_f32_16x16x32_bf16 v[48:51], v[152:155], v[186:189], v[48:51]
	v_mfma_f32_16x16x32_bf16 v[36:39], v[144:147], v[194:197], v[36:39]
	v_mfma_f32_16x16x32_bf16 v[32:35], v[152:155], v[194:197], v[32:35]
	v_mfma_f32_16x16x32_bf16 v[20:23], v[144:147], v[202:205], v[20:23]
	v_mfma_f32_16x16x32_bf16 v[16:19], v[152:155], v[202:205], v[16:19]
	v_mfma_f32_16x16x32_bf16 v[4:7], v[144:147], v[210:213], v[4:7]
	v_mfma_f32_16x16x32_bf16 v[0:3], v[152:155], v[210:213], v[0:3]
	v_mfma_f32_16x16x32_bf16 v[52:55], v[148:151], v[190:193], v[52:55]
	v_mfma_f32_16x16x32_bf16 v[48:51], v[156:159], v[190:193], v[48:51]
	v_mfma_f32_16x16x32_bf16 v[36:39], v[148:151], v[198:201], v[36:39]
	v_mfma_f32_16x16x32_bf16 v[32:35], v[156:159], v[198:201], v[32:35]
	v_mfma_f32_16x16x32_bf16 v[20:23], v[148:151], v[206:209], v[20:23]
	v_mfma_f32_16x16x32_bf16 v[16:19], v[156:159], v[206:209], v[16:19]
	v_mfma_f32_16x16x32_bf16 v[4:7], v[148:151], v[214:217], v[4:7]
	v_mfma_f32_16x16x32_bf16 v[0:3], v[156:159], v[214:217], v[0:3]
	s_barrier
	s_add_i32 s40, s92, 2
	s_cmp_gt_u32 s92, 13
	s_mov_b32 s92, s40
	s_cbranch_scc1 .LBB0_1928

.LBB0_2160:
	s_add_u32 s28, s8, s26
	s_addc_u32 s29, s9, s27
	s_add_u32 s28, s28, 0x100
	s_addc_u32 s29, s29, 0
	s_add_u32 s40, s56, s26
	s_addc_u32 s41, s57, s27
	s_add_i32 s63, 0, 0x10000
	v_add_u32_e32 v145, s63, v143
	ds_read_b128 v[146:149], v145
	ds_read_b128 v[150:153], v145 offset:1024
	ds_read_b128 v[154:157], v145 offset:2048
	ds_read_b128 v[162:165], v145 offset:3072
	s_cmpk_eq_i32 s26, 0x1f00
	s_cselect_b32 s31, s13, s29
	s_cselect_b32 s30, s60, s28
	s_cselect_b32 s29, s11, s41
	s_cselect_b32 s28, s61, s40
	v_lshl_add_u64 v[158:159], v[140:141], 0, s[26:27]
	s_add_i32 m0, s23, 0xc000
	ds_read_b128 v[168:171], v144
	ds_read_b128 v[172:175], v144 offset:1024
	ds_read_b128 v[178:181], v144 offset:2048
	ds_read_b128 v[182:185], v144 offset:3072
	ds_read_b128 v[186:189], v144 offset:4096
	ds_read_b128 v[190:193], v144 offset:5120
	ds_read_b128 v[196:199], v144 offset:6144
	ds_read_b128 v[200:203], v144 offset:7168
	global_load_lds_dwordx4 v[158:159], off
	v_lshl_add_u64 v[158:159], v[138:139], 0, s[26:27]
	s_add_i32 m0, s23, 0xe000
	s_nop 0
	global_load_lds_dwordx4 v[158:159], off
	s_waitcnt lgkmcnt(8)
	s_barrier
	s_waitcnt lgkmcnt(0)
	s_waitcnt lgkmcnt(0)
	v_mfma_f32_16x16x32_bf16 v[120:123], v[146:149], v[168:171], v[120:123]
	v_mfma_f32_16x16x32_bf16 v[124:127], v[154:157], v[168:171], v[124:127]
	v_mfma_f32_16x16x32_bf16 v[108:111], v[146:149], v[178:181], v[108:111]
	v_mfma_f32_16x16x32_bf16 v[104:107], v[154:157], v[178:181], v[104:107]
	v_mfma_f32_16x16x32_bf16 v[92:95], v[146:149], v[186:189], v[92:95]
	v_mfma_f32_16x16x32_bf16 v[88:91], v[154:157], v[186:189], v[88:91]
	v_mfma_f32_16x16x32_bf16 v[76:79], v[146:149], v[196:199], v[76:79]
	v_mfma_f32_16x16x32_bf16 v[72:75], v[154:157], v[196:199], v[72:75]
	v_mfma_f32_16x16x32_bf16 v[120:123], v[150:153], v[172:175], v[120:123]
	v_mfma_f32_16x16x32_bf16 v[124:127], v[162:165], v[172:175], v[124:127]
	v_mfma_f32_16x16x32_bf16 v[108:111], v[150:153], v[182:185], v[108:111]
	v_mfma_f32_16x16x32_bf16 v[104:107], v[162:165], v[182:185], v[104:107]
	v_mfma_f32_16x16x32_bf16 v[92:95], v[150:153], v[190:193], v[92:95]
	v_mfma_f32_16x16x32_bf16 v[88:91], v[162:165], v[190:193], v[88:91]
	v_mfma_f32_16x16x32_bf16 v[76:79], v[150:153], v[200:203], v[76:79]
	v_mfma_f32_16x16x32_bf16 v[72:75], v[162:165], v[200:203], v[72:75]
	s_barrier
	s_add_i32 s64, 0, 0x14000
	s_add_i32 s40, s63, s3
	v_add_u32_e32 v145, s64, v143
	v_lshl_add_u64 v[158:159], s[28:29], 0, v[160:161]
	s_mov_b32 m0, s40
	ds_read_b128 v[204:207], v145
	ds_read_b128 v[208:211], v145 offset:1024
	ds_read_b128 v[212:215], v145 offset:2048
	ds_read_b128 v[216:219], v145 offset:3072
	global_load_lds_dwordx4 v[158:159], off
	v_lshl_add_u64 v[220:221], s[28:29], 0, v[128:129]
	s_add_i32 m0, s40, 0x2000
	s_nop 0
	global_load_lds_dwordx4 v[220:221], off
	s_barrier
	s_waitcnt lgkmcnt(0)
	s_waitcnt lgkmcnt(0)
	v_mfma_f32_16x16x32_bf16 v[116:119], v[204:207], v[168:171], v[116:119]
	v_mfma_f32_16x16x32_bf16 v[112:115], v[212:215], v[168:171], v[112:115]
	v_mfma_f32_16x16x32_bf16 v[100:103], v[204:207], v[178:181], v[100:103]
	v_mfma_f32_16x16x32_bf16 v[96:99], v[212:215], v[178:181], v[96:99]
	v_mfma_f32_16x16x32_bf16 v[84:87], v[204:207], v[186:189], v[84:87]
	v_mfma_f32_16x16x32_bf16 v[80:83], v[212:215], v[186:189], v[80:83]
	v_mfma_f32_16x16x32_bf16 v[68:71], v[204:207], v[196:199], v[68:71]
	v_mfma_f32_16x16x32_bf16 v[64:67], v[212:215], v[196:199], v[64:67]
	v_mfma_f32_16x16x32_bf16 v[116:119], v[208:211], v[172:175], v[116:119]
	v_mfma_f32_16x16x32_bf16 v[112:115], v[216:219], v[172:175], v[112:115]
	v_mfma_f32_16x16x32_bf16 v[100:103], v[208:211], v[182:185], v[100:103]
	v_mfma_f32_16x16x32_bf16 v[96:99], v[216:219], v[182:185], v[96:99]
	v_mfma_f32_16x16x32_bf16 v[84:87], v[208:211], v[190:193], v[84:87]
	v_mfma_f32_16x16x32_bf16 v[80:83], v[216:219], v[190:193], v[80:83]
	v_mfma_f32_16x16x32_bf16 v[68:71], v[208:211], v[200:203], v[68:71]
	v_mfma_f32_16x16x32_bf16 v[64:67], v[216:219], v[200:203], v[64:67]
	s_mov_b32 m0, s23
	v_lshl_add_u64 v[222:223], s[30:31], 0, v[132:133]
	s_barrier
	ds_read_b128 v[168:171], v144 offset:16384
	ds_read_b128 v[172:175], v144 offset:17408
	ds_read_b128 v[178:181], v144 offset:18432
	ds_read_b128 v[182:185], v144 offset:19456
	ds_read_b128 v[186:189], v144 offset:20480
	ds_read_b128 v[190:193], v144 offset:21504
	ds_read_b128 v[196:199], v144 offset:22528
	ds_read_b128 v[200:203], v144 offset:23552
	global_load_lds_dwordx4 v[222:223], off
	v_lshl_add_u64 v[224:225], s[30:31], 0, v[130:131]
	s_mov_b32 m0, s35
	s_nop 0
	global_load_lds_dwordx4 v[224:225], off
	s_barrier
	s_waitcnt lgkmcnt(0)
	s_waitcnt lgkmcnt(0)
	v_mfma_f32_16x16x32_bf16 v[60:63], v[146:149], v[168:171], v[60:63]
	v_mfma_f32_16x16x32_bf16 v[56:59], v[154:157], v[168:171], v[56:59]
	v_mfma_f32_16x16x32_bf16 v[44:47], v[146:149], v[178:181], v[44:47]
	v_mfma_f32_16x16x32_bf16 v[40:43], v[154:157], v[178:181], v[40:43]
	v_mfma_f32_16x16x32_bf16 v[28:31], v[146:149], v[186:189], v[28:31]
	v_mfma_f32_16x16x32_bf16 v[24:27], v[154:157], v[186:189], v[24:27]
	v_mfma_f32_16x16x32_bf16 v[12:15], v[146:149], v[196:199], v[12:15]
	v_mfma_f32_16x16x32_bf16 v[8:11], v[154:157], v[196:199], v[8:11]
	v_mfma_f32_16x16x32_bf16 v[60:63], v[150:153], v[172:175], v[60:63]
	v_mfma_f32_16x16x32_bf16 v[56:59], v[162:165], v[172:175], v[56:59]
	v_mfma_f32_16x16x32_bf16 v[44:47], v[150:153], v[182:185], v[44:47]
	v_mfma_f32_16x16x32_bf16 v[40:43], v[162:165], v[182:185], v[40:43]
	v_mfma_f32_16x16x32_bf16 v[28:31], v[150:153], v[190:193], v[28:31]
	v_mfma_f32_16x16x32_bf16 v[24:27], v[162:165], v[190:193], v[24:27]
	v_mfma_f32_16x16x32_bf16 v[12:15], v[150:153], v[200:203], v[12:15]
	v_mfma_f32_16x16x32_bf16 v[8:11], v[162:165], v[200:203], v[8:11]
	s_barrier
	s_add_u32 s40, s28, 0x100000
	s_addc_u32 s41, s29, 0
	s_add_i32 s63, s64, s3
	v_lshl_add_u64 v[146:147], s[40:41], 0, v[160:161]
	s_mov_b32 m0, s63
	s_nop 0
	global_load_lds_dwordx4 v[146:147], off
	v_lshl_add_u64 v[146:147], s[40:41], 0, v[128:129]
	s_add_i32 m0, s63, 0x2000
	s_nop 0
	global_load_lds_dwordx4 v[146:147], off
	s_waitcnt vmcnt(6)
	s_barrier
	v_mfma_f32_16x16x32_bf16 v[52:55], v[204:207], v[168:171], v[52:55]
	v_mfma_f32_16x16x32_bf16 v[48:51], v[212:215], v[168:171], v[48:51]
	v_mfma_f32_16x16x32_bf16 v[36:39], v[204:207], v[178:181], v[36:39]
	v_mfma_f32_16x16x32_bf16 v[32:35], v[212:215], v[178:181], v[32:35]
	v_mfma_f32_16x16x32_bf16 v[20:23], v[204:207], v[186:189], v[20:23]
	v_mfma_f32_16x16x32_bf16 v[16:19], v[212:215], v[186:189], v[16:19]
	v_mfma_f32_16x16x32_bf16 v[4:7], v[204:207], v[196:199], v[4:7]
	v_mfma_f32_16x16x32_bf16 v[0:3], v[212:215], v[196:199], v[0:3]
	v_mfma_f32_16x16x32_bf16 v[52:55], v[208:211], v[172:175], v[52:55]
	v_mfma_f32_16x16x32_bf16 v[48:51], v[216:219], v[172:175], v[48:51]
	v_mfma_f32_16x16x32_bf16 v[36:39], v[208:211], v[182:185], v[36:39]
	v_mfma_f32_16x16x32_bf16 v[32:35], v[216:219], v[182:185], v[32:35]
	v_mfma_f32_16x16x32_bf16 v[20:23], v[208:211], v[190:193], v[20:23]
	v_mfma_f32_16x16x32_bf16 v[16:19], v[216:219], v[190:193], v[16:19]
	v_mfma_f32_16x16x32_bf16 v[4:7], v[208:211], v[200:203], v[4:7]
	v_mfma_f32_16x16x32_bf16 v[0:3], v[216:219], v[200:203], v[0:3]
	s_add_i32 s40, 0, 0x18000
	v_add_u32_e32 v145, s40, v143
	s_barrier
	ds_read_b128 v[146:149], v145
	ds_read_b128 v[150:153], v145 offset:1024
	ds_read_b128 v[154:157], v145 offset:2048
	ds_read_b128 v[162:165], v145 offset:3072
	s_add_u32 s30, s30, 0x100000
	s_addc_u32 s31, s31, 0
	s_mov_b32 m0, s44
	v_lshl_add_u64 v[204:205], s[30:31], 0, v[132:133]
	ds_read_b128 v[168:171], v144 offset:32768
	ds_read_b128 v[172:175], v144 offset:33792
	ds_read_b128 v[178:181], v144 offset:34816
	ds_read_b128 v[182:185], v144 offset:35840
	ds_read_b128 v[186:189], v144 offset:36864
	ds_read_b128 v[190:193], v144 offset:37888
	ds_read_b128 v[196:199], v144 offset:38912
	ds_read_b128 v[200:203], v144 offset:39936
	global_load_lds_dwordx4 v[204:205], off
	v_lshl_add_u64 v[204:205], s[30:31], 0, v[130:131]
	s_mov_b32 m0, s46
	s_nop 0
	global_load_lds_dwordx4 v[204:205], off
	s_waitcnt lgkmcnt(8)
	s_barrier
	s_waitcnt lgkmcnt(0)
	s_waitcnt lgkmcnt(0)
	v_mfma_f32_16x16x32_bf16 v[120:123], v[146:149], v[168:171], v[120:123]
	v_mfma_f32_16x16x32_bf16 v[124:127], v[154:157], v[168:171], v[124:127]
	v_mfma_f32_16x16x32_bf16 v[108:111], v[146:149], v[178:181], v[108:111]
	v_mfma_f32_16x16x32_bf16 v[104:107], v[154:157], v[178:181], v[104:107]
	v_mfma_f32_16x16x32_bf16 v[92:95], v[146:149], v[186:189], v[92:95]
	v_mfma_f32_16x16x32_bf16 v[88:91], v[154:157], v[186:189], v[88:91]
	v_mfma_f32_16x16x32_bf16 v[76:79], v[146:149], v[196:199], v[76:79]
	v_mfma_f32_16x16x32_bf16 v[72:75], v[154:157], v[196:199], v[72:75]
	v_mfma_f32_16x16x32_bf16 v[120:123], v[150:153], v[172:175], v[120:123]
	v_mfma_f32_16x16x32_bf16 v[124:127], v[162:165], v[172:175], v[124:127]
	v_mfma_f32_16x16x32_bf16 v[108:111], v[150:153], v[182:185], v[108:111]
	v_mfma_f32_16x16x32_bf16 v[104:107], v[162:165], v[182:185], v[104:107]
	v_mfma_f32_16x16x32_bf16 v[92:95], v[150:153], v[190:193], v[92:95]
	v_mfma_f32_16x16x32_bf16 v[88:91], v[162:165], v[190:193], v[88:91]
	v_mfma_f32_16x16x32_bf16 v[76:79], v[150:153], v[200:203], v[76:79]
	v_mfma_f32_16x16x32_bf16 v[72:75], v[162:165], v[200:203], v[72:75]
	s_barrier
	s_add_i32 s30, 0, 0x1c000
	s_add_i32 s31, s40, s3
	v_add_u32_e32 v145, s30, v143
	v_lshl_add_u64 v[158:159], v[158:159], 0, s[50:51]
	s_mov_b32 m0, s31
	ds_read_b128 v[204:207], v145
	ds_read_b128 v[208:211], v145 offset:1024
	ds_read_b128 v[212:215], v145 offset:2048
	ds_read_b128 v[216:219], v145 offset:3072
	global_load_lds_dwordx4 v[158:159], off
	v_lshl_add_u64 v[158:159], v[220:221], 0, s[50:51]
	s_add_i32 m0, s31, 0x2000
	s_nop 0
	global_load_lds_dwordx4 v[158:159], off
	s_barrier
	s_waitcnt lgkmcnt(0)
	s_waitcnt lgkmcnt(0)
	v_mfma_f32_16x16x32_bf16 v[116:119], v[204:207], v[168:171], v[116:119]
	v_mfma_f32_16x16x32_bf16 v[112:115], v[212:215], v[168:171], v[112:115]
	v_mfma_f32_16x16x32_bf16 v[100:103], v[204:207], v[178:181], v[100:103]
	v_mfma_f32_16x16x32_bf16 v[96:99], v[212:215], v[178:181], v[96:99]
	v_mfma_f32_16x16x32_bf16 v[84:87], v[204:207], v[186:189], v[84:87]
	v_mfma_f32_16x16x32_bf16 v[80:83], v[212:215], v[186:189], v[80:83]
	v_mfma_f32_16x16x32_bf16 v[68:71], v[204:207], v[196:199], v[68:71]
	v_mfma_f32_16x16x32_bf16 v[64:67], v[212:215], v[196:199], v[64:67]
	v_mfma_f32_16x16x32_bf16 v[116:119], v[208:211], v[172:175], v[116:119]
	v_mfma_f32_16x16x32_bf16 v[112:115], v[216:219], v[172:175], v[112:115]
	v_mfma_f32_16x16x32_bf16 v[100:103], v[208:211], v[182:185], v[100:103]
	v_mfma_f32_16x16x32_bf16 v[96:99], v[216:219], v[182:185], v[96:99]
	v_mfma_f32_16x16x32_bf16 v[84:87], v[208:211], v[190:193], v[84:87]
	v_mfma_f32_16x16x32_bf16 v[80:83], v[216:219], v[190:193], v[80:83]
	v_mfma_f32_16x16x32_bf16 v[68:71], v[208:211], v[200:203], v[68:71]
	v_mfma_f32_16x16x32_bf16 v[64:67], v[216:219], v[200:203], v[64:67]
	s_mov_b32 m0, s47
	v_lshl_add_u64 v[158:159], v[222:223], 0, s[50:51]
	s_barrier
	ds_read_b128 v[168:171], v144 offset:49152
	ds_read_b128 v[172:175], v144 offset:50176
	ds_read_b128 v[178:181], v144 offset:51200
	ds_read_b128 v[182:185], v144 offset:52224
	ds_read_b128 v[186:189], v144 offset:53248
	ds_read_b128 v[190:193], v144 offset:54272
	ds_read_b128 v[196:199], v144 offset:55296
	ds_read_b128 v[200:203], v144 offset:56320
	global_load_lds_dwordx4 v[158:159], off
	v_lshl_add_u64 v[158:159], v[224:225], 0, s[50:51]
	s_mov_b32 m0, s48
	s_nop 0
	global_load_lds_dwordx4 v[158:159], off
	s_barrier
	s_waitcnt lgkmcnt(0)
	s_waitcnt lgkmcnt(0)
	v_mfma_f32_16x16x32_bf16 v[60:63], v[146:149], v[168:171], v[60:63]
	v_mfma_f32_16x16x32_bf16 v[56:59], v[154:157], v[168:171], v[56:59]
	v_mfma_f32_16x16x32_bf16 v[44:47], v[146:149], v[178:181], v[44:47]
	v_mfma_f32_16x16x32_bf16 v[40:43], v[154:157], v[178:181], v[40:43]
	v_mfma_f32_16x16x32_bf16 v[28:31], v[146:149], v[186:189], v[28:31]
	v_mfma_f32_16x16x32_bf16 v[24:27], v[154:157], v[186:189], v[24:27]
	v_mfma_f32_16x16x32_bf16 v[12:15], v[146:149], v[196:199], v[12:15]
	v_mfma_f32_16x16x32_bf16 v[8:11], v[154:157], v[196:199], v[8:11]
	v_mfma_f32_16x16x32_bf16 v[60:63], v[150:153], v[172:175], v[60:63]
	v_mfma_f32_16x16x32_bf16 v[56:59], v[162:165], v[172:175], v[56:59]
	v_mfma_f32_16x16x32_bf16 v[44:47], v[150:153], v[182:185], v[44:47]
	v_mfma_f32_16x16x32_bf16 v[40:43], v[162:165], v[182:185], v[40:43]
	v_mfma_f32_16x16x32_bf16 v[28:31], v[150:153], v[190:193], v[28:31]
	v_mfma_f32_16x16x32_bf16 v[24:27], v[162:165], v[190:193], v[24:27]
	v_mfma_f32_16x16x32_bf16 v[12:15], v[150:153], v[200:203], v[12:15]
	v_mfma_f32_16x16x32_bf16 v[8:11], v[162:165], v[200:203], v[8:11]
	s_barrier
	s_add_u32 s28, s28, 0x100080
	s_addc_u32 s29, s29, 0
	s_add_i32 s30, s30, s3
	v_lshl_add_u64 v[146:147], s[28:29], 0, v[160:161]
	s_mov_b32 m0, s30
	s_nop 0
	global_load_lds_dwordx4 v[146:147], off
	v_lshl_add_u64 v[146:147], s[28:29], 0, v[128:129]
	s_add_i32 m0, s30, 0x2000
	s_nop 0
	global_load_lds_dwordx4 v[146:147], off
	s_waitcnt vmcnt(6)
	s_barrier
	v_mfma_f32_16x16x32_bf16 v[52:55], v[204:207], v[168:171], v[52:55]
	v_mfma_f32_16x16x32_bf16 v[48:51], v[212:215], v[168:171], v[48:51]
	v_mfma_f32_16x16x32_bf16 v[36:39], v[204:207], v[178:181], v[36:39]
	v_mfma_f32_16x16x32_bf16 v[32:35], v[212:215], v[178:181], v[32:35]
	v_mfma_f32_16x16x32_bf16 v[20:23], v[204:207], v[186:189], v[20:23]
	v_mfma_f32_16x16x32_bf16 v[16:19], v[212:215], v[186:189], v[16:19]
	v_mfma_f32_16x16x32_bf16 v[4:7], v[204:207], v[196:199], v[4:7]
	v_mfma_f32_16x16x32_bf16 v[0:3], v[212:215], v[196:199], v[0:3]
	v_mfma_f32_16x16x32_bf16 v[52:55], v[208:211], v[172:175], v[52:55]
	v_mfma_f32_16x16x32_bf16 v[48:51], v[216:219], v[172:175], v[48:51]
	v_mfma_f32_16x16x32_bf16 v[36:39], v[208:211], v[182:185], v[36:39]
	v_mfma_f32_16x16x32_bf16 v[32:35], v[216:219], v[182:185], v[32:35]
	v_mfma_f32_16x16x32_bf16 v[20:23], v[208:211], v[190:193], v[20:23]
	v_mfma_f32_16x16x32_bf16 v[16:19], v[216:219], v[190:193], v[16:19]
	v_mfma_f32_16x16x32_bf16 v[4:7], v[208:211], v[200:203], v[4:7]
	v_mfma_f32_16x16x32_bf16 v[0:3], v[216:219], v[200:203], v[0:3]
	s_add_i32 s62, s62, 2
	s_add_u32 s26, s26, 0x100
	s_addc_u32 s27, s27, 0
	s_cmp_gt_u32 s62, 61
	s_barrier
	s_cbranch_scc0 .LBB0_2160
	s_add_u32 s26, s56, 0xffffff00
	s_addc_u32 s27, s57, -1
	s_andn2_b64 vcc, exec, s[6:7]
	s_cbranch_vccnz .LBB0_2163
	v_mov_b32_e32 v0, 0
	s_mov_b32 s22, s10
	s_mov_b32 s20, s12
	s_mov_b64 s[8:9], s[24:25]
	s_mov_b32 s49, s52
	v_mov_b32_e32 v1, v0
	v_mov_b32_e32 v2, v0
	v_mov_b32_e32 v3, v0
	v_mov_b32_e32 v4, v0
	v_mov_b32_e32 v5, v0
	v_mov_b32_e32 v6, v0
	v_mov_b32_e32 v7, v0
	v_mov_b32_e32 v16, v0
	v_mov_b32_e32 v17, v0
	v_mov_b32_e32 v18, v0
	v_mov_b32_e32 v19, v0
	v_mov_b32_e32 v20, v0
	v_mov_b32_e32 v21, v0
	v_mov_b32_e32 v22, v0
	v_mov_b32_e32 v23, v0
	v_mov_b32_e32 v32, v0
	v_mov_b32_e32 v33, v0
	v_mov_b32_e32 v34, v0
	v_mov_b32_e32 v35, v0
	v_mov_b32_e32 v36, v0
	v_mov_b32_e32 v37, v0
	v_mov_b32_e32 v38, v0
	v_mov_b32_e32 v39, v0
	v_mov_b32_e32 v48, v0
	v_mov_b32_e32 v49, v0
	v_mov_b32_e32 v50, v0
	v_mov_b32_e32 v51, v0
	v_mov_b32_e32 v52, v0
	v_mov_b32_e32 v53, v0
	v_mov_b32_e32 v54, v0
	v_mov_b32_e32 v55, v0
	v_mov_b32_e32 v8, v0
	v_mov_b32_e32 v9, v0
	v_mov_b32_e32 v10, v0
	v_mov_b32_e32 v11, v0
	v_mov_b32_e32 v12, v0
	v_mov_b32_e32 v13, v0
	v_mov_b32_e32 v14, v0
	v_mov_b32_e32 v15, v0
	v_mov_b32_e32 v24, v0
	v_mov_b32_e32 v25, v0
	v_mov_b32_e32 v26, v0
	v_mov_b32_e32 v27, v0
	v_mov_b32_e32 v28, v0
	v_mov_b32_e32 v29, v0
	v_mov_b32_e32 v30, v0
	v_mov_b32_e32 v31, v0
	v_mov_b32_e32 v40, v0
	v_mov_b32_e32 v41, v0
	v_mov_b32_e32 v42, v0
	v_mov_b32_e32 v43, v0
	v_mov_b32_e32 v44, v0
	v_mov_b32_e32 v45, v0
	v_mov_b32_e32 v46, v0
	v_mov_b32_e32 v47, v0
	v_mov_b32_e32 v56, v0
	v_mov_b32_e32 v57, v0
	v_mov_b32_e32 v58, v0
	v_mov_b32_e32 v59, v0
	v_mov_b32_e32 v60, v0
	v_mov_b32_e32 v61, v0
	v_mov_b32_e32 v62, v0
	v_mov_b32_e32 v63, v0
	v_mov_b32_e32 v64, v0
	v_mov_b32_e32 v65, v0
	v_mov_b32_e32 v66, v0
	v_mov_b32_e32 v67, v0
	v_mov_b32_e32 v68, v0
	v_mov_b32_e32 v69, v0
	v_mov_b32_e32 v70, v0
	v_mov_b32_e32 v71, v0
	v_mov_b32_e32 v80, v0
	v_mov_b32_e32 v81, v0
	v_mov_b32_e32 v82, v0
	v_mov_b32_e32 v83, v0
	v_mov_b32_e32 v84, v0
	v_mov_b32_e32 v85, v0
	v_mov_b32_e32 v86, v0
	v_mov_b32_e32 v87, v0
	v_mov_b32_e32 v96, v0
	v_mov_b32_e32 v97, v0
	v_mov_b32_e32 v98, v0
	v_mov_b32_e32 v99, v0
	v_mov_b32_e32 v100, v0
	v_mov_b32_e32 v101, v0
	v_mov_b32_e32 v102, v0
	v_mov_b32_e32 v103, v0
	v_mov_b32_e32 v112, v0
	v_mov_b32_e32 v113, v0
	v_mov_b32_e32 v114, v0
	v_mov_b32_e32 v115, v0
	v_mov_b32_e32 v116, v0
	v_mov_b32_e32 v117, v0
	v_mov_b32_e32 v118, v0
	v_mov_b32_e32 v119, v0
	v_mov_b32_e32 v72, v0
	v_mov_b32_e32 v73, v0
	v_mov_b32_e32 v74, v0
	v_mov_b32_e32 v75, v0
	v_mov_b32_e32 v76, v0
	v_mov_b32_e32 v77, v0
	v_mov_b32_e32 v78, v0
	v_mov_b32_e32 v79, v0
	v_mov_b32_e32 v88, v0
	v_mov_b32_e32 v89, v0
	v_mov_b32_e32 v90, v0
	v_mov_b32_e32 v91, v0
	v_mov_b32_e32 v92, v0
	v_mov_b32_e32 v93, v0
	v_mov_b32_e32 v94, v0
	v_mov_b32_e32 v95, v0
	v_mov_b32_e32 v104, v0
	v_mov_b32_e32 v105, v0
	v_mov_b32_e32 v106, v0
	v_mov_b32_e32 v107, v0
	v_mov_b32_e32 v108, v0
	v_mov_b32_e32 v109, v0
	v_mov_b32_e32 v110, v0
	v_mov_b32_e32 v111, v0
	v_mov_b32_e32 v124, v0
	v_mov_b32_e32 v125, v0
	v_mov_b32_e32 v126, v0
	v_mov_b32_e32 v127, v0
	v_mov_b32_e32 v120, v0
	v_mov_b32_e32 v121, v0
	v_mov_b32_e32 v122, v0
	v_mov_b32_e32 v123, v0
	s_andn2_b64 vcc, exec, s[4:5]
	s_cbranch_vccnz .LBB0_2164
	s_branch .LBB0_2165
